# loop-tail scalar adds moved into H1 MFMA gaps, duplicate vmcnt wait removed
# speedup vs baseline: 1.0170x; 1.0073x over previous
; #define MFMA16(a, b, c) __builtin_amdgcn_mfma_f32_16x16x32_bf16((a), (b), (c), 0, 0, 0)
;     ...
;   for (int kt = 0; kt < nk; ++kt) {
;     const int buf = kt & 1;
;     const char* cA = smem + buf * STAGE + (wm * 32 * MI + r16) * 128;
;     const char* cB = smem + buf * STAGE + 32768 + (wn * 64 + r16) * 128;
; #pragma unroll
;     for (int k2 = 0; k2 < 2; ++k2) {
;       if (k2 == 1 && kt + 1 < nk) STAGE_TILE(buf ^ 1, (kt + 1) * 64)
;       const int po = ((4 * k2 + q4) ^ swz) * 16;
;       bf16x8 bf[4];
; #pragma unroll
;       for (int nt = 0; nt < 4; ++nt) bf[nt] = *(const bf16x8*)(cB + nt * 16 * 128 + po);
;       bf16x8 afc = *(const bf16x8*)(cA + po);
; #pragma unroll
;       for (int a = 0; a < MT; ++a) {
;         bf16x8 afn = afc;
;         if (a + 1 < MT) afn = *(const bf16x8*)(cA + (a + 1) * 16 * 128 + po);
;         __builtin_amdgcn_sched_barrier(0);
; #pragma unroll
;         for (int nt = 0; nt < 4; ++nt) acc[a][nt] = MFMA16(bf[nt], afc, acc[a][nt]);
;         __builtin_amdgcn_sched_barrier(0);
;         afc = afn;
;       }
;     }
;     asm volatile("s_waitcnt vmcnt(0)" ::: "memory");
;     __syncthreads();
;   }
.LBB0_48:
	s_and_b32 s42, s41, 0x10000
	s_add_i32 s43, s42, 0
	s_xor_b32 s42, s42, 0x10000
	v_add_u32_e32 v174, s43, v147
	v_add_u32_e32 v162, v174, v146
	v_add_u32_e32 v149, s43, v148
	ds_read_b128 v[150:153], v162 offset:32768
	ds_read_b128 v[154:157], v162 offset:34816
	ds_read_b128 v[158:161], v162 offset:36864
	ds_read_b128 v[162:165], v162 offset:38912
	v_add_u32_e32 v175, v149, v146
	ds_read_b128 v[166:169], v175
	ds_read_b128 v[170:173], v175 offset:2048
	s_waitcnt lgkmcnt(1)
	v_mfma_f32_16x16x32_bf16 v[126:129], v[150:153], v[166:169], v[126:129]
	v_readfirstlane_b32 s43, v145
	v_mfma_f32_16x16x32_bf16 v[122:125], v[154:157], v[166:169], v[122:125]
	s_nop 0
	v_mfma_f32_16x16x32_bf16 v[118:121], v[158:161], v[166:169], v[118:121]
	s_add_u32 s43, s43, s42
	v_mfma_f32_16x16x32_bf16 v[114:117], v[162:165], v[166:169], v[114:117]
	ds_read_b128 v[166:169], v175 offset:4096
	s_waitcnt lgkmcnt(1)
	v_mfma_f32_16x16x32_bf16 v[110:113], v[150:153], v[170:173], v[110:113]
	s_add_u32 m0, s43, 0x0
	v_mfma_f32_16x16x32_bf16 v[106:109], v[154:157], v[170:173], v[106:109]
	global_load_lds_dwordx4 v176, s[100:101]
	v_mfma_f32_16x16x32_bf16 v[102:105], v[158:161], v[170:173], v[102:105]
	s_add_u32 m0, s43, 0x2000
	v_mfma_f32_16x16x32_bf16 v[98:101], v[162:165], v[170:173], v[98:101]
	ds_read_b128 v[170:173], v175 offset:6144
	s_waitcnt lgkmcnt(1)
	v_mfma_f32_16x16x32_bf16 v[94:97], v[150:153], v[166:169], v[94:97]
	global_load_lds_dwordx4 v177, s[100:101]
	v_mfma_f32_16x16x32_bf16 v[90:93], v[154:157], v[166:169], v[90:93]
	s_add_u32 m0, s43, 0x4000
	v_mfma_f32_16x16x32_bf16 v[86:89], v[158:161], v[166:169], v[86:89]
	global_load_lds_dwordx4 v178, s[100:101]
	v_mfma_f32_16x16x32_bf16 v[82:85], v[162:165], v[166:169], v[82:85]
	ds_read_b128 v[166:169], v175 offset:8192
	s_waitcnt lgkmcnt(1)
	v_mfma_f32_16x16x32_bf16 v[78:81], v[150:153], v[170:173], v[78:81]
	s_add_u32 m0, s43, 0x6000
	v_mfma_f32_16x16x32_bf16 v[74:77], v[154:157], v[170:173], v[74:77]
	global_load_lds_dwordx4 v179, s[100:101]
	v_mfma_f32_16x16x32_bf16 v[70:73], v[158:161], v[170:173], v[70:73]
	s_add_u32 m0, s43, 0x8000
	v_mfma_f32_16x16x32_bf16 v[66:69], v[162:165], v[170:173], v[66:69]
	ds_read_b128 v[170:173], v175 offset:10240
	s_waitcnt lgkmcnt(1)
	v_mfma_f32_16x16x32_bf16 v[62:65], v[150:153], v[166:169], v[62:65]
	global_load_lds_dwordx4 v180, s[100:101]
	v_mfma_f32_16x16x32_bf16 v[58:61], v[154:157], v[166:169], v[58:61]
	s_add_u32 m0, s43, 0xa000
	v_mfma_f32_16x16x32_bf16 v[54:57], v[158:161], v[166:169], v[54:57]
	global_load_lds_dwordx4 v181, s[100:101]
	v_mfma_f32_16x16x32_bf16 v[50:53], v[162:165], v[166:169], v[50:53]
	ds_read_b128 v[166:169], v175 offset:12288
	s_waitcnt lgkmcnt(1)
	v_mfma_f32_16x16x32_bf16 v[46:49], v[150:153], v[170:173], v[46:49]
	s_add_u32 m0, s43, 0xc000
	v_mfma_f32_16x16x32_bf16 v[42:45], v[154:157], v[170:173], v[42:45]
	global_load_lds_dwordx4 v182, s[100:101]
	v_mfma_f32_16x16x32_bf16 v[38:41], v[158:161], v[170:173], v[38:41]
	s_add_u32 m0, s43, 0xe000
	v_mfma_f32_16x16x32_bf16 v[34:37], v[162:165], v[170:173], v[34:37]
	ds_read_b128 v[170:173], v175 offset:14336
	s_waitcnt lgkmcnt(1)
	v_mfma_f32_16x16x32_bf16 v[30:33], v[150:153], v[166:169], v[30:33]
	global_load_lds_dwordx4 v183, s[100:101]
	v_mfma_f32_16x16x32_bf16 v[26:29], v[154:157], v[166:169], v[26:29]
	v_mfma_f32_16x16x32_bf16 v[22:25], v[158:161], v[166:169], v[22:25]
	v_mfma_f32_16x16x32_bf16 v[18:21], v[162:165], v[166:169], v[18:21]
	s_waitcnt lgkmcnt(0)
	v_mfma_f32_16x16x32_bf16 v[14:17], v[150:153], v[170:173], v[14:17]
	v_mfma_f32_16x16x32_bf16 v[10:13], v[154:157], v[170:173], v[10:13]
	v_mfma_f32_16x16x32_bf16 v[6:9], v[158:161], v[170:173], v[6:9]
	v_mfma_f32_16x16x32_bf16 v[2:5], v[162:165], v[170:173], v[2:5]
	v_add_u32_e32 v162, v174, v144
	ds_read_b128 v[150:153], v162 offset:32768
	ds_read_b128 v[154:157], v162 offset:34816
	ds_read_b128 v[158:161], v162 offset:36864
	ds_read_b128 v[162:165], v162 offset:38912
	v_add_u32_e32 v149, v149, v144
	ds_read_b128 v[166:169], v149
	ds_read_b128 v[170:173], v149 offset:2048
	s_waitcnt lgkmcnt(0)
	v_mfma_f32_16x16x32_bf16 v[126:129], v[150:153], v[166:169], v[126:129]
	s_add_u32 s100, s100, 0x80
	v_mfma_f32_16x16x32_bf16 v[122:125], v[154:157], v[166:169], v[122:125]
	s_addc_u32 s101, s101, 0
	v_mfma_f32_16x16x32_bf16 v[118:121], v[158:161], v[166:169], v[118:121]
	s_add_u32 s16, s16, 0x80
	v_mfma_f32_16x16x32_bf16 v[114:117], v[162:165], v[166:169], v[114:117]
	ds_read_b128 v[166:169], v149 offset:4096
	v_mfma_f32_16x16x32_bf16 v[110:113], v[150:153], v[170:173], v[110:113]
	s_addc_u32 s17, s17, 0
	v_mfma_f32_16x16x32_bf16 v[106:109], v[154:157], v[170:173], v[106:109]
	s_add_i32 s41, s41, 0x10000
	v_mfma_f32_16x16x32_bf16 v[102:105], v[158:161], v[170:173], v[102:105]
	v_mfma_f32_16x16x32_bf16 v[98:101], v[162:165], v[170:173], v[98:101]
	ds_read_b128 v[170:173], v149 offset:6144
	s_waitcnt lgkmcnt(0)
	v_mfma_f32_16x16x32_bf16 v[94:97], v[150:153], v[166:169], v[94:97]
	v_mfma_f32_16x16x32_bf16 v[90:93], v[154:157], v[166:169], v[90:93]
	v_mfma_f32_16x16x32_bf16 v[86:89], v[158:161], v[166:169], v[86:89]
	v_mfma_f32_16x16x32_bf16 v[82:85], v[162:165], v[166:169], v[82:85]
	ds_read_b128 v[166:169], v149 offset:8192
	v_mfma_f32_16x16x32_bf16 v[78:81], v[150:153], v[170:173], v[78:81]
	v_mfma_f32_16x16x32_bf16 v[74:77], v[154:157], v[170:173], v[74:77]
	v_mfma_f32_16x16x32_bf16 v[70:73], v[158:161], v[170:173], v[70:73]
	v_mfma_f32_16x16x32_bf16 v[66:69], v[162:165], v[170:173], v[66:69]
	ds_read_b128 v[170:173], v149 offset:10240
	s_waitcnt lgkmcnt(0)
	v_mfma_f32_16x16x32_bf16 v[62:65], v[150:153], v[166:169], v[62:65]
	v_mfma_f32_16x16x32_bf16 v[58:61], v[154:157], v[166:169], v[58:61]
	v_mfma_f32_16x16x32_bf16 v[54:57], v[158:161], v[166:169], v[54:57]
	v_mfma_f32_16x16x32_bf16 v[50:53], v[162:165], v[166:169], v[50:53]
	ds_read_b128 v[166:169], v149 offset:12288
	v_mfma_f32_16x16x32_bf16 v[46:49], v[150:153], v[170:173], v[46:49]
	v_mfma_f32_16x16x32_bf16 v[42:45], v[154:157], v[170:173], v[42:45]
	v_mfma_f32_16x16x32_bf16 v[38:41], v[158:161], v[170:173], v[38:41]
	v_mfma_f32_16x16x32_bf16 v[34:37], v[162:165], v[170:173], v[34:37]
	ds_read_b128 v[170:173], v149 offset:14336
	s_waitcnt lgkmcnt(0)
	v_mfma_f32_16x16x32_bf16 v[30:33], v[150:153], v[166:169], v[30:33]
	v_mfma_f32_16x16x32_bf16 v[26:29], v[154:157], v[166:169], v[26:29]
	v_mfma_f32_16x16x32_bf16 v[22:25], v[158:161], v[166:169], v[22:25]
	v_mfma_f32_16x16x32_bf16 v[18:21], v[162:165], v[166:169], v[18:21]
	v_mfma_f32_16x16x32_bf16 v[14:17], v[150:153], v[170:173], v[14:17]
	v_mfma_f32_16x16x32_bf16 v[10:13], v[154:157], v[170:173], v[10:13]
	v_mfma_f32_16x16x32_bf16 v[6:9], v[158:161], v[170:173], v[6:9]
	v_mfma_f32_16x16x32_bf16 v[2:5], v[162:165], v[170:173], v[2:5]
	s_cmpk_eq_i32 s16, 0x1580
	s_waitcnt vmcnt(0)
	s_barrier
; #define MFMA16(a, b, c) __builtin_amdgcn_mfma_f32_16x16x32_bf16((a), (b), (c), 0, 0, 0)
;     ...
;   for (int kt = 0; kt < nk; ++kt) {
;     const int buf = kt & 1;
;     const char* cA = smem + buf * STAGE + (wm * 32 * MI + r16) * 128;
;     const char* cB = smem + buf * STAGE + 32768 + (wn * 64 + r16) * 128;
; #pragma unroll
;     for (int k2 = 0; k2 < 2; ++k2) {
;       if (k2 == 1 && kt + 1 < nk) STAGE_TILE(buf ^ 1, (kt + 1) * 64)
;       const int po = ((4 * k2 + q4) ^ swz) * 16;
;       bf16x8 bf[4];
; #pragma unroll
;       for (int nt = 0; nt < 4; ++nt) bf[nt] = *(const bf16x8*)(cB + nt * 16 * 128 + po);
;       bf16x8 afc = *(const bf16x8*)(cA + po);
; #pragma unroll
;       for (int a = 0; a < MT; ++a) {
;         bf16x8 afn = afc;
;         if (a + 1 < MT) afn = *(const bf16x8*)(cA + (a + 1) * 16 * 128 + po);
;         __builtin_amdgcn_sched_barrier(0);
; #pragma unroll
;         for (int nt = 0; nt < 4; ++nt) acc[a][nt] = MFMA16(bf[nt], afc, acc[a][nt]);
;         __builtin_amdgcn_sched_barrier(0);
;         afc = afn;
;       }
;     }
	s_cbranch_scc0 .LBB0_48
	s_add_i32 s16, 0, 0x10000
	v_add_u32_e32 v138, s16, v148
	v_readlane_b32 s16, v254, 18
	s_nop 1
	v_add_u32_e32 v139, s16, v147
	v_add_u32_e32 v145, v139, v146
	ds_read_b128 v[130:133], v145
	ds_read_b128 v[134:137], v145 offset:2048
	ds_read_b128 v[148:151], v145 offset:4096
	ds_read_b128 v[152:155], v145 offset:6144
	v_add_u32_e32 v145, v138, v146
	ds_read_b128 v[156:159], v145
	ds_read_b128 v[160:163], v145 offset:2048
	s_waitcnt lgkmcnt(1)
	v_mfma_f32_16x16x32_bf16 v[126:129], v[130:133], v[156:159], v[126:129]
	v_mfma_f32_16x16x32_bf16 v[122:125], v[134:137], v[156:159], v[122:125]
	v_mfma_f32_16x16x32_bf16 v[118:121], v[148:151], v[156:159], v[118:121]
	v_mfma_f32_16x16x32_bf16 v[114:117], v[152:155], v[156:159], v[114:117]
	ds_read_b128 v[156:159], v145 offset:4096
	s_waitcnt lgkmcnt(1)
	v_mfma_f32_16x16x32_bf16 v[110:113], v[130:133], v[160:163], v[110:113]
	v_mfma_f32_16x16x32_bf16 v[106:109], v[134:137], v[160:163], v[106:109]
	v_mfma_f32_16x16x32_bf16 v[102:105], v[148:151], v[160:163], v[102:105]
	v_mfma_f32_16x16x32_bf16 v[98:101], v[152:155], v[160:163], v[98:101]
	ds_read_b128 v[160:163], v145 offset:6144
	s_waitcnt lgkmcnt(1)
	v_mfma_f32_16x16x32_bf16 v[94:97], v[130:133], v[156:159], v[94:97]
	v_mfma_f32_16x16x32_bf16 v[90:93], v[134:137], v[156:159], v[90:93]
	v_mfma_f32_16x16x32_bf16 v[86:89], v[148:151], v[156:159], v[86:89]
	v_mfma_f32_16x16x32_bf16 v[82:85], v[152:155], v[156:159], v[82:85]
	ds_read_b128 v[156:159], v145 offset:8192
	s_waitcnt lgkmcnt(1)
	v_mfma_f32_16x16x32_bf16 v[78:81], v[130:133], v[160:163], v[78:81]
	v_mfma_f32_16x16x32_bf16 v[74:77], v[134:137], v[160:163], v[74:77]
	v_mfma_f32_16x16x32_bf16 v[70:73], v[148:151], v[160:163], v[70:73]
	v_mfma_f32_16x16x32_bf16 v[66:69], v[152:155], v[160:163], v[66:69]
	ds_read_b128 v[160:163], v145 offset:10240
	s_waitcnt lgkmcnt(1)
	v_mfma_f32_16x16x32_bf16 v[62:65], v[130:133], v[156:159], v[62:65]
	v_mfma_f32_16x16x32_bf16 v[58:61], v[134:137], v[156:159], v[58:61]
	v_mfma_f32_16x16x32_bf16 v[54:57], v[148:151], v[156:159], v[54:57]
	v_mfma_f32_16x16x32_bf16 v[50:53], v[152:155], v[156:159], v[50:53]
	ds_read_b128 v[156:159], v145 offset:12288
	s_waitcnt lgkmcnt(1)
	v_mfma_f32_16x16x32_bf16 v[46:49], v[130:133], v[160:163], v[46:49]
	v_mfma_f32_16x16x32_bf16 v[42:45], v[134:137], v[160:163], v[42:45]
	v_mfma_f32_16x16x32_bf16 v[38:41], v[148:151], v[160:163], v[38:41]
	v_mfma_f32_16x16x32_bf16 v[34:37], v[152:155], v[160:163], v[34:37]
	ds_read_b128 v[160:163], v145 offset:14336
	s_waitcnt lgkmcnt(1)
	v_mfma_f32_16x16x32_bf16 v[30:33], v[130:133], v[156:159], v[30:33]
	v_mfma_f32_16x16x32_bf16 v[26:29], v[134:137], v[156:159], v[26:29]
	v_mfma_f32_16x16x32_bf16 v[22:25], v[148:151], v[156:159], v[22:25]
	v_mfma_f32_16x16x32_bf16 v[18:21], v[152:155], v[156:159], v[18:21]
	s_waitcnt lgkmcnt(0)
	v_mfma_f32_16x16x32_bf16 v[14:17], v[130:133], v[160:163], v[14:17]
	v_mfma_f32_16x16x32_bf16 v[10:13], v[134:137], v[160:163], v[10:13]
	v_mfma_f32_16x16x32_bf16 v[6:9], v[148:151], v[160:163], v[6:9]
	v_mfma_f32_16x16x32_bf16 v[2:5], v[152:155], v[160:163], v[2:5]
	v_add_u32_e32 v139, v139, v144
	ds_read_b128 v[130:133], v139
	ds_read_b128 v[134:137], v139 offset:2048
	ds_read_b128 v[146:149], v139 offset:4096
	ds_read_b128 v[150:153], v139 offset:6144
	v_add_u32_e32 v138, v138, v144
	ds_read_b128 v[154:157], v138
	ds_read_b128 v[158:161], v138 offset:2048
	s_waitcnt lgkmcnt(1)
	v_mfma_f32_16x16x32_bf16 v[126:129], v[130:133], v[154:157], v[126:129]
	v_mfma_f32_16x16x32_bf16 v[122:125], v[134:137], v[154:157], v[122:125]
	v_mfma_f32_16x16x32_bf16 v[118:121], v[146:149], v[154:157], v[118:121]
	v_mfma_f32_16x16x32_bf16 v[114:117], v[150:153], v[154:157], v[114:117]
	ds_read_b128 v[154:157], v138 offset:4096
	s_waitcnt lgkmcnt(1)
	v_mfma_f32_16x16x32_bf16 v[110:113], v[130:133], v[158:161], v[110:113]
	v_mfma_f32_16x16x32_bf16 v[106:109], v[134:137], v[158:161], v[106:109]
	v_mfma_f32_16x16x32_bf16 v[102:105], v[146:149], v[158:161], v[102:105]
	v_mfma_f32_16x16x32_bf16 v[98:101], v[150:153], v[158:161], v[98:101]
	ds_read_b128 v[158:161], v138 offset:6144
	s_waitcnt lgkmcnt(1)
	v_mfma_f32_16x16x32_bf16 v[94:97], v[130:133], v[154:157], v[94:97]
	v_mfma_f32_16x16x32_bf16 v[90:93], v[134:137], v[154:157], v[90:93]
	v_mfma_f32_16x16x32_bf16 v[86:89], v[146:149], v[154:157], v[86:89]
	v_mfma_f32_16x16x32_bf16 v[82:85], v[150:153], v[154:157], v[82:85]
	ds_read_b128 v[154:157], v138 offset:8192
	s_waitcnt lgkmcnt(1)
	v_mfma_f32_16x16x32_bf16 v[78:81], v[130:133], v[158:161], v[78:81]
	v_mfma_f32_16x16x32_bf16 v[74:77], v[134:137], v[158:161], v[74:77]
	v_mfma_f32_16x16x32_bf16 v[70:73], v[146:149], v[158:161], v[70:73]
	v_mfma_f32_16x16x32_bf16 v[66:69], v[150:153], v[158:161], v[66:69]
	ds_read_b128 v[158:161], v138 offset:10240
	s_waitcnt lgkmcnt(1)
	v_mfma_f32_16x16x32_bf16 v[62:65], v[130:133], v[154:157], v[62:65]
	v_mfma_f32_16x16x32_bf16 v[58:61], v[134:137], v[154:157], v[58:61]
	v_mfma_f32_16x16x32_bf16 v[54:57], v[146:149], v[154:157], v[54:57]
	v_mfma_f32_16x16x32_bf16 v[50:53], v[150:153], v[154:157], v[50:53]
	ds_read_b128 v[154:157], v138 offset:12288
	s_waitcnt lgkmcnt(1)
	v_mfma_f32_16x16x32_bf16 v[46:49], v[130:133], v[158:161], v[46:49]
	v_mfma_f32_16x16x32_bf16 v[42:45], v[134:137], v[158:161], v[42:45]
	v_mfma_f32_16x16x32_bf16 v[38:41], v[146:149], v[158:161], v[38:41]
	v_mfma_f32_16x16x32_bf16 v[34:37], v[150:153], v[158:161], v[34:37]
	ds_read_b128 v[158:161], v138 offset:14336
	s_waitcnt lgkmcnt(1)
;     ...
;     for (int a = 0; a < MT; ++a) ep(row0 + 16 * a, cbw, q4, acc[a][0], acc[a][1], acc[a][2], acc[a][3]);
;   } else {
; #pragma unroll
;     for (int a = 0; a < MT; ++a)
; #pragma unroll
;       for (int nt = 0; nt < 4; ++nt)
;         ep(row0 + 16 * a, cbw + 16 * nt + 4 * q4, acc[a][nt][0], acc[a][nt][1], acc[a][nt][2], acc[a][nt][3]);
; DI void phase_resid(char* smem, const Params& p, int layer, const bf16_t* A, int K, const bf16_t* W, int gate_idx, bool first) {
;     ...
;   auto ep = [&](int row, int col, float v0, float v1, float v2, float v3) {
;     const int b = row / TT, t = row - b * TT;
;     const float4 g = *(const float4*)(p.mod + (size_t)(layer * 5 + (t < CTXL ? 4 : b)) * 6144 + gate_idx * 1024 + col);
;     const float4 xo = *(const float4*)(xsrc_row(p, first, row) + col);
;     *(float4*)(xdst_row(p, row) + col) = make_float4(xo.x + g.x * v0, xo.y + g.y * v1, xo.z + g.z * v2, xo.w + g.w * v3);
;   };
	v_mfma_f32_16x16x32_bf16 v[30:33], v[130:133], v[154:157], v[30:33]
	v_mfma_f32_16x16x32_bf16 v[26:29], v[134:137], v[154:157], v[26:29]
	v_mfma_f32_16x16x32_bf16 v[22:25], v[146:149], v[154:157], v[22:25]
	v_mfma_f32_16x16x32_bf16 v[18:21], v[150:153], v[154:157], v[18:21]
	s_waitcnt lgkmcnt(0)
	v_mfma_f32_16x16x32_bf16 v[14:17], v[130:133], v[158:161], v[14:17]
	v_mfma_f32_16x16x32_bf16 v[10:13], v[134:137], v[158:161], v[10:13]
	v_mfma_f32_16x16x32_bf16 v[6:9], v[146:149], v[158:161], v[6:9]
	v_mfma_f32_16x16x32_bf16 v[2:5], v[150:153], v[158:161], v[2:5]
	v_or_b32_e32 v131, s40, v142
	v_lshlrev_b32_e32 v130, 6, v143
	v_lshl_add_u32 v142, v140, 7, v131
	v_lshlrev_b32_e32 v131, 2, v141
	v_or3_b32 v134, v130, v131, s39
	v_mul_hi_i32 v130, v142, s1
	v_lshrrev_b32_e32 v131, 31, v130
	v_ashrrev_i32_e32 v130, 11, v130
	v_add_u32_e32 v130, v130, v131
	v_mad_i32_i24 v131, v130, s90, v142
	s_movk_i32 s39, 0x100
	v_cmp_gt_i32_e32 vcc, s39, v131
	v_add_u32_e32 v132, 0xffffff00, v131
	v_ashrrev_i32_e32 v133, 31, v131
	v_readlane_b32 s40, v254, 1
	v_cndmask_b32_e64 v135, v130, 4, vcc
	v_cndmask_b32_e32 v133, 0, v133, vcc
	v_cndmask_b32_e32 v132, v132, v131, vcc
	v_ashrrev_i32_e32 v131, 31, v130
	v_cndmask_b32_e64 v136, 25, 20, vcc
	v_readlane_b32 s41, v254, 2
	v_lshlrev_b64 v[140:141], v136, v[130:131]
	v_lshlrev_b64 v[150:151], 12, v[132:133]
	v_add_u32_e32 v130, s37, v135
	v_mov_b64_e32 v[132:133], s[40:41]
	s_movk_i32 s40, 0x6000
	v_readlane_b32 s42, v254, 3
	v_readlane_b32 s43, v254, 4
	v_mad_i64_i32 v[130:131], s[16:17], v130, s40, v[132:133]
	s_mov_b64 s[42:43], 0x5000
	v_ashrrev_i32_e32 v135, 31, v134
	v_readlane_b32 s16, v252, 26
	v_lshl_add_u64 v[136:137], v[130:131], 0, s[42:43]
	v_lshlrev_b64 v[130:131], 2, v[134:135]
	v_mov_b32_e32 v135, s16
	v_readlane_b32 s16, v252, 28
	s_waitcnt vmcnt(0)
	s_barrier
	s_nop 0
	v_mov_b32_e32 v143, s16
	v_readlane_b32 s16, v252, 25
	v_cndmask_b32_e32 v139, v135, v143, vcc
	s_nop 0
	v_mov_b32_e32 v144, s16
	v_readlane_b32 s16, v252, 27
	v_readlane_b32 s68, v252, 5
	v_readlane_b32 s80, v252, 17
	v_mov_b32_e32 v145, s16
	v_cndmask_b32_e32 v138, v144, v145, vcc
	global_load_dwordx2 v[138:139], v[138:139], off
	v_readlane_b32 s81, v252, 18
	v_readlane_b32 s82, v252, 19
	v_readlane_b32 s83, v252, 20
	v_mov_b32_e32 v146, s81
	v_mov_b32_e32 v148, s80
	v_mov_b32_e32 v147, s83
	v_mov_b32_e32 v149, s82
	v_cndmask_b32_e32 v155, v146, v147, vcc
	v_cndmask_b32_e32 v154, v148, v149, vcc
	v_lshl_add_u64 v[152:153], v[136:137], 0, v[130:131]
	s_add_i32 s38, s38, s30
	s_cmp_gt_i32 s38, 31
	v_readlane_b32 s44, v254, 5
	v_readlane_b32 s45, v254, 6
	v_readlane_b32 s46, v254, 7
	v_readlane_b32 s47, v254, 8
	v_readlane_b32 s48, v254, 9
	v_readlane_b32 s49, v254, 10
	v_readlane_b32 s50, v254, 11
	v_readlane_b32 s51, v254, 12
	v_readlane_b32 s52, v254, 13
	v_readlane_b32 s53, v254, 14
	v_readlane_b32 s54, v254, 15
	v_readlane_b32 s55, v254, 16
	v_readlane_b32 s69, v252, 6
	v_readlane_b32 s70, v252, 7
	v_readlane_b32 s71, v252, 8
	v_readlane_b32 s72, v252, 9
	v_readlane_b32 s73, v252, 10
	v_readlane_b32 s74, v252, 11
	v_readlane_b32 s75, v252, 12
	v_readlane_b32 s76, v252, 13
	v_readlane_b32 s77, v252, 14
	v_readlane_b32 s78, v252, 15
	v_readlane_b32 s79, v252, 16
	s_waitcnt vmcnt(0)
	v_lshl_add_u64 v[138:139], v[138:139], 0, v[140:141]
	v_lshl_add_u64 v[138:139], v[138:139], 0, v[150:151]
	v_lshl_add_u64 v[140:141], v[154:155], 0, v[140:141]
	v_lshl_add_u64 v[138:139], v[138:139], 0, v[130:131]
	v_lshl_add_u64 v[140:141], v[140:141], 0, v[150:151]
	v_lshl_add_u64 v[140:141], v[140:141], 0, v[130:131]
	s_cselect_b64 s[16:17], -1, 0
	global_load_dwordx4 v[156:159], v[152:153], off
	global_load_dwordx4 v[160:163], v[152:153], off offset:64
	global_load_dwordx4 v[164:167], v[152:153], off offset:128
	global_load_dwordx4 v[168:171], v[152:153], off offset:192
	global_load_dwordx4 v[172:175], v[138:139], off
	global_load_dwordx4 v[176:179], v[138:139], off offset:64
	global_load_dwordx4 v[180:183], v[138:139], off offset:128
	global_load_dwordx4 v[184:187], v[138:139], off offset:192
	v_add_co_u32_e32 v138, vcc, 0x10000, v138
	s_nop 1
	v_addc_co_u32_e32 v139, vcc, 0, v139, vcc
	global_load_dwordx4 v[198:201], v[138:139], off
	global_load_dwordx4 v[202:205], v[138:139], off offset:64
	global_load_dwordx4 v[206:209], v[138:139], off offset:128
	global_load_dwordx4 v[210:213], v[138:139], off offset:192
	v_add_co_u32_e32 v138, vcc, 0x10000, v138
	s_nop 1
	v_addc_co_u32_e32 v139, vcc, 0, v139, vcc
	global_load_dwordx4 v[214:217], v[138:139], off
	global_load_dwordx4 v[218:221], v[138:139], off offset:64
	global_load_dwordx4 v[222:225], v[138:139], off offset:128
	global_load_dwordx4 v[142:145], v[138:139], off offset:192
	v_add_co_u32_e32 v138, vcc, 0x10000, v138
	s_nop 1
	v_addc_co_u32_e32 v139, vcc, 0, v139, vcc
	s_waitcnt vmcnt(8)
	v_pk_fma_f32 v[126:127], v[126:127], v[156:157], v[172:173]
	v_pk_fma_f32 v[128:129], v[128:129], v[158:159], v[174:175]
	v_pk_fma_f32 v[122:123], v[122:123], v[160:161], v[176:177]
	v_pk_fma_f32 v[124:125], v[124:125], v[162:163], v[178:179]
	v_pk_fma_f32 v[118:119], v[118:119], v[164:165], v[180:181]
	v_pk_fma_f32 v[120:121], v[120:121], v[166:167], v[182:183]
	v_pk_fma_f32 v[114:115], v[114:115], v[168:169], v[184:185]
	v_pk_fma_f32 v[116:117], v[116:117], v[170:171], v[186:187]
	global_store_dwordx4 v[140:141], v[126:129], off
	global_store_dwordx4 v[140:141], v[122:125], off offset:64
	global_store_dwordx4 v[140:141], v[118:121], off offset:128
	global_store_dwordx4 v[140:141], v[114:117], off offset:192
	v_add_co_u32_e32 v140, vcc, 0x10000, v140
	s_nop 1
	v_addc_co_u32_e32 v141, vcc, 0, v141, vcc
	global_load_dwordx4 v[172:175], v[138:139], off
	global_load_dwordx4 v[176:179], v[138:139], off offset:64
	global_load_dwordx4 v[180:183], v[138:139], off offset:128
	global_load_dwordx4 v[184:187], v[138:139], off offset:192
	v_add_co_u32_e32 v138, vcc, 0x10000, v138
	s_nop 1
	v_addc_co_u32_e32 v139, vcc, 0, v139, vcc
	s_waitcnt vmcnt(12)
;     ...
; #pragma unroll
;     for (int a = 0; a < MT; ++a)
; #pragma unroll
;       for (int nt = 0; nt < 4; ++nt)
;         ep(row0 + 16 * a, cbw + 16 * nt + 4 * q4, acc[a][nt][0], acc[a][nt][1], acc[a][nt][2], acc[a][nt][3]);
; DI void phase_resid(char* smem, const Params& p, int layer, const bf16_t* A, int K, const bf16_t* W, int gate_idx, bool first) {
;     ...
;   auto ep = [&](int row, int col, float v0, float v1, float v2, float v3) {
;     const int b = row / TT, t = row - b * TT;
;     const float4 g = *(const float4*)(p.mod + (size_t)(layer * 5 + (t < CTXL ? 4 : b)) * 6144 + gate_idx * 1024 + col);
;     const float4 xo = *(const float4*)(xsrc_row(p, first, row) + col);
;     *(float4*)(xdst_row(p, row) + col) = make_float4(xo.x + g.x * v0, xo.y + g.y * v1, xo.z + g.z * v2, xo.w + g.w * v3);
;   };
	v_pk_fma_f32 v[110:111], v[110:111], v[156:157], v[198:199]
	v_pk_fma_f32 v[112:113], v[112:113], v[158:159], v[200:201]
	v_pk_fma_f32 v[106:107], v[106:107], v[160:161], v[202:203]
	v_pk_fma_f32 v[108:109], v[108:109], v[162:163], v[204:205]
	v_pk_fma_f32 v[102:103], v[102:103], v[164:165], v[206:207]
	v_pk_fma_f32 v[104:105], v[104:105], v[166:167], v[208:209]
	v_pk_fma_f32 v[98:99], v[98:99], v[168:169], v[210:211]
	v_pk_fma_f32 v[100:101], v[100:101], v[170:171], v[212:213]
	global_store_dwordx4 v[140:141], v[110:113], off
	global_store_dwordx4 v[140:141], v[106:109], off offset:64
	global_store_dwordx4 v[140:141], v[102:105], off offset:128
	global_store_dwordx4 v[140:141], v[98:101], off offset:192
	v_add_co_u32_e32 v140, vcc, 0x10000, v140
	s_nop 1
	v_addc_co_u32_e32 v141, vcc, 0, v141, vcc
	global_load_dwordx4 v[198:201], v[138:139], off
	global_load_dwordx4 v[202:205], v[138:139], off offset:64
	global_load_dwordx4 v[206:209], v[138:139], off offset:128
	global_load_dwordx4 v[210:213], v[138:139], off offset:192
	v_add_co_u32_e32 v138, vcc, 0x10000, v138
	s_nop 1
	v_addc_co_u32_e32 v139, vcc, 0, v139, vcc
	s_waitcnt vmcnt(16)
	v_pk_fma_f32 v[94:95], v[94:95], v[156:157], v[214:215]
	v_pk_fma_f32 v[96:97], v[96:97], v[158:159], v[216:217]
	v_pk_fma_f32 v[90:91], v[90:91], v[160:161], v[218:219]
	v_pk_fma_f32 v[92:93], v[92:93], v[162:163], v[220:221]
	v_pk_fma_f32 v[86:87], v[86:87], v[164:165], v[222:223]
	v_pk_fma_f32 v[88:89], v[88:89], v[166:167], v[224:225]
	v_pk_fma_f32 v[82:83], v[82:83], v[168:169], v[142:143]
	v_pk_fma_f32 v[84:85], v[84:85], v[170:171], v[144:145]
	global_store_dwordx4 v[140:141], v[94:97], off
	global_store_dwordx4 v[140:141], v[90:93], off offset:64
	global_store_dwordx4 v[140:141], v[86:89], off offset:128
	global_store_dwordx4 v[140:141], v[82:85], off offset:192
	v_add_co_u32_e32 v140, vcc, 0x10000, v140
	s_nop 1
	v_addc_co_u32_e32 v141, vcc, 0, v141, vcc
	global_load_dwordx4 v[214:217], v[138:139], off
	global_load_dwordx4 v[218:221], v[138:139], off offset:64
	global_load_dwordx4 v[222:225], v[138:139], off offset:128
	global_load_dwordx4 v[142:145], v[138:139], off offset:192
	v_add_co_u32_e32 v138, vcc, 0x10000, v138
	s_nop 1
	v_addc_co_u32_e32 v139, vcc, 0, v139, vcc
	s_waitcnt vmcnt(16)
	v_pk_fma_f32 v[78:79], v[78:79], v[156:157], v[172:173]
	v_pk_fma_f32 v[80:81], v[80:81], v[158:159], v[174:175]
	v_pk_fma_f32 v[74:75], v[74:75], v[160:161], v[176:177]
	v_pk_fma_f32 v[76:77], v[76:77], v[162:163], v[178:179]
	v_pk_fma_f32 v[70:71], v[70:71], v[164:165], v[180:181]
	v_pk_fma_f32 v[72:73], v[72:73], v[166:167], v[182:183]
	v_pk_fma_f32 v[66:67], v[66:67], v[168:169], v[184:185]
	v_pk_fma_f32 v[68:69], v[68:69], v[170:171], v[186:187]
	global_store_dwordx4 v[140:141], v[78:81], off
	global_store_dwordx4 v[140:141], v[74:77], off offset:64
	global_store_dwordx4 v[140:141], v[70:73], off offset:128
	global_store_dwordx4 v[140:141], v[66:69], off offset:192
	v_add_co_u32_e32 v140, vcc, 0x10000, v140
	s_nop 1
	v_addc_co_u32_e32 v141, vcc, 0, v141, vcc
	global_load_dwordx4 v[172:175], v[138:139], off
	global_load_dwordx4 v[176:179], v[138:139], off offset:64
	global_load_dwordx4 v[180:183], v[138:139], off offset:128
	global_load_dwordx4 v[184:187], v[138:139], off offset:192
	v_add_co_u32_e32 v138, vcc, 0x10000, v138
	s_nop 1
	v_addc_co_u32_e32 v139, vcc, 0, v139, vcc
	s_waitcnt vmcnt(16)
	v_pk_fma_f32 v[62:63], v[62:63], v[156:157], v[198:199]
	v_pk_fma_f32 v[64:65], v[64:65], v[158:159], v[200:201]
	v_pk_fma_f32 v[58:59], v[58:59], v[160:161], v[202:203]
	v_pk_fma_f32 v[60:61], v[60:61], v[162:163], v[204:205]
	v_pk_fma_f32 v[54:55], v[54:55], v[164:165], v[206:207]
	v_pk_fma_f32 v[56:57], v[56:57], v[166:167], v[208:209]
	v_pk_fma_f32 v[50:51], v[50:51], v[168:169], v[210:211]
	v_pk_fma_f32 v[52:53], v[52:53], v[170:171], v[212:213]
	global_store_dwordx4 v[140:141], v[62:65], off
	global_store_dwordx4 v[140:141], v[58:61], off offset:64
	global_store_dwordx4 v[140:141], v[54:57], off offset:128
	global_store_dwordx4 v[140:141], v[50:53], off offset:192
	v_add_co_u32_e32 v140, vcc, 0x10000, v140
	s_nop 1
	v_addc_co_u32_e32 v141, vcc, 0, v141, vcc
	global_load_dwordx4 v[198:201], v[138:139], off
	global_load_dwordx4 v[202:205], v[138:139], off offset:64
	global_load_dwordx4 v[206:209], v[138:139], off offset:128
	global_load_dwordx4 v[210:213], v[138:139], off offset:192
	s_waitcnt vmcnt(16)
	v_pk_fma_f32 v[46:47], v[46:47], v[156:157], v[214:215]
	v_pk_fma_f32 v[48:49], v[48:49], v[158:159], v[216:217]
	v_pk_fma_f32 v[42:43], v[42:43], v[160:161], v[218:219]
	v_pk_fma_f32 v[44:45], v[44:45], v[162:163], v[220:221]
	v_pk_fma_f32 v[38:39], v[38:39], v[164:165], v[222:223]
	v_pk_fma_f32 v[40:41], v[40:41], v[166:167], v[224:225]
	v_pk_fma_f32 v[34:35], v[34:35], v[168:169], v[142:143]
	v_pk_fma_f32 v[36:37], v[36:37], v[170:171], v[144:145]
	global_store_dwordx4 v[140:141], v[46:49], off
	global_store_dwordx4 v[140:141], v[42:45], off offset:64
	global_store_dwordx4 v[140:141], v[38:41], off offset:128
	global_store_dwordx4 v[140:141], v[34:37], off offset:192
	v_add_co_u32_e32 v140, vcc, 0x10000, v140
	s_nop 1
	v_addc_co_u32_e32 v141, vcc, 0, v141, vcc
	s_waitcnt vmcnt(12)
	v_pk_fma_f32 v[30:31], v[30:31], v[156:157], v[172:173]
	v_pk_fma_f32 v[32:33], v[32:33], v[158:159], v[174:175]
	v_pk_fma_f32 v[26:27], v[26:27], v[160:161], v[176:177]
	v_pk_fma_f32 v[28:29], v[28:29], v[162:163], v[178:179]
	v_pk_fma_f32 v[22:23], v[22:23], v[164:165], v[180:181]
	v_pk_fma_f32 v[24:25], v[24:25], v[166:167], v[182:183]
	v_pk_fma_f32 v[18:19], v[18:19], v[168:169], v[184:185]
	v_pk_fma_f32 v[20:21], v[20:21], v[170:171], v[186:187]
	global_store_dwordx4 v[140:141], v[30:33], off
	global_store_dwordx4 v[140:141], v[26:29], off offset:64
	global_store_dwordx4 v[140:141], v[22:25], off offset:128
	global_store_dwordx4 v[140:141], v[18:21], off offset:192
	v_add_co_u32_e32 v140, vcc, 0x10000, v140
	s_nop 1
	v_addc_co_u32_e32 v141, vcc, 0, v141, vcc
	s_waitcnt vmcnt(8)
	v_pk_fma_f32 v[14:15], v[14:15], v[156:157], v[198:199]
	v_pk_fma_f32 v[16:17], v[16:17], v[158:159], v[200:201]
	v_pk_fma_f32 v[10:11], v[10:11], v[160:161], v[202:203]
	v_pk_fma_f32 v[12:13], v[12:13], v[162:163], v[204:205]
	v_pk_fma_f32 v[6:7], v[6:7], v[164:165], v[206:207]
	v_pk_fma_f32 v[8:9], v[8:9], v[166:167], v[208:209]
	v_pk_fma_f32 v[2:3], v[2:3], v[168:169], v[210:211]
	v_pk_fma_f32 v[4:5], v[4:5], v[170:171], v[212:213]
	global_store_dwordx4 v[140:141], v[14:17], off
	global_store_dwordx4 v[140:141], v[10:13], off offset:64
	global_store_dwordx4 v[140:141], v[6:9], off offset:128
	global_store_dwordx4 v[140:141], v[2:5], off offset:192
	s_branch .LBB0_41

; #define MFMA16(a, b, c) __builtin_amdgcn_mfma_f32_16x16x32_bf16((a), (b), (c), 0, 0, 0)
;     ...
;   for (int kt = 0; kt < nk; ++kt) {
;     const int buf = kt & 1;
;     const char* cA = smem + buf * STAGE + (wm * 32 * MI + r16) * 128;
;     const char* cB = smem + buf * STAGE + 32768 + (wn * 64 + r16) * 128;
; #pragma unroll
;     for (int k2 = 0; k2 < 2; ++k2) {
;       if (k2 == 1 && kt + 1 < nk) STAGE_TILE(buf ^ 1, (kt + 1) * 64)
;       const int po = ((4 * k2 + q4) ^ swz) * 16;
;       bf16x8 bf[4];
; #pragma unroll
;       for (int nt = 0; nt < 4; ++nt) bf[nt] = *(const bf16x8*)(cB + nt * 16 * 128 + po);
;       bf16x8 afc = *(const bf16x8*)(cA + po);
; #pragma unroll
;       for (int a = 0; a < MT; ++a) {
;         bf16x8 afn = afc;
;         if (a + 1 < MT) afn = *(const bf16x8*)(cA + (a + 1) * 16 * 128 + po);
;         __builtin_amdgcn_sched_barrier(0);
; #pragma unroll
;         for (int nt = 0; nt < 4; ++nt) acc[a][nt] = MFMA16(bf[nt], afc, acc[a][nt]);
;         __builtin_amdgcn_sched_barrier(0);
;         afc = afn;
;       }
;     }
;     asm volatile("s_waitcnt vmcnt(0)" ::: "memory");
;     __syncthreads();
;   }
.LBB0_75:
	s_and_b32 s41, s40, 0x10000
	s_add_i32 s42, s41, 0
	v_add_u32_e32 v190, s42, v147
	v_add_u32_e32 v162, v190, v146
	v_add_u32_e32 v149, s42, v148
	ds_read_b128 v[150:153], v162 offset:32768
	ds_read_b128 v[154:157], v162 offset:34816
	ds_read_b128 v[158:161], v162 offset:36864
	ds_read_b128 v[162:165], v162 offset:38912
	v_add_u32_e32 v202, v149, v146
	ds_read_b128 v[166:169], v202
	ds_read_b128 v[170:173], v202 offset:2048
	s_xor_b32 s41, s41, 0x10000
	s_waitcnt lgkmcnt(1)
	v_mfma_f32_16x16x32_bf16 v[126:129], v[150:153], v[166:169], v[126:129]
	v_readfirstlane_b32 s42, v145
	v_mfma_f32_16x16x32_bf16 v[122:125], v[154:157], v[166:169], v[122:125]
	s_nop 0
	v_mfma_f32_16x16x32_bf16 v[118:121], v[158:161], v[166:169], v[118:121]
	s_add_u32 s42, s42, s41
	v_mfma_f32_16x16x32_bf16 v[114:117], v[162:165], v[166:169], v[114:117]
	ds_read_b128 v[166:169], v202 offset:4096
	s_waitcnt lgkmcnt(1)
	v_mfma_f32_16x16x32_bf16 v[110:113], v[150:153], v[170:173], v[110:113]
	s_add_u32 m0, s42, 0x0
	v_mfma_f32_16x16x32_bf16 v[106:109], v[154:157], v[170:173], v[106:109]
	global_load_lds_dwordx4 v174, s[100:101]
	v_mfma_f32_16x16x32_bf16 v[102:105], v[158:161], v[170:173], v[102:105]
	s_add_u32 m0, s42, 0x2000
	v_mfma_f32_16x16x32_bf16 v[98:101], v[162:165], v[170:173], v[98:101]
	ds_read_b128 v[170:173], v202 offset:6144
	s_waitcnt lgkmcnt(1)
	v_mfma_f32_16x16x32_bf16 v[94:97], v[150:153], v[166:169], v[94:97]
	global_load_lds_dwordx4 v175, s[100:101]
	v_mfma_f32_16x16x32_bf16 v[90:93], v[154:157], v[166:169], v[90:93]
	s_add_u32 m0, s42, 0x4000
	v_mfma_f32_16x16x32_bf16 v[86:89], v[158:161], v[166:169], v[86:89]
	global_load_lds_dwordx4 v176, s[100:101]
	v_mfma_f32_16x16x32_bf16 v[82:85], v[162:165], v[166:169], v[82:85]
	ds_read_b128 v[166:169], v202 offset:8192
	s_waitcnt lgkmcnt(1)
	v_mfma_f32_16x16x32_bf16 v[78:81], v[150:153], v[170:173], v[78:81]
	s_add_u32 m0, s42, 0x6000
	v_mfma_f32_16x16x32_bf16 v[74:77], v[154:157], v[170:173], v[74:77]
	global_load_lds_dwordx4 v177, s[100:101]
	v_mfma_f32_16x16x32_bf16 v[70:73], v[158:161], v[170:173], v[70:73]
	s_add_u32 m0, s42, 0x8000
	v_mfma_f32_16x16x32_bf16 v[66:69], v[162:165], v[170:173], v[66:69]
	ds_read_b128 v[170:173], v202 offset:10240
	s_waitcnt lgkmcnt(1)
	v_mfma_f32_16x16x32_bf16 v[62:65], v[150:153], v[166:169], v[62:65]
	global_load_lds_dwordx4 v178, s[100:101]
	v_mfma_f32_16x16x32_bf16 v[58:61], v[154:157], v[166:169], v[58:61]
	s_add_u32 m0, s42, 0xa000
	v_mfma_f32_16x16x32_bf16 v[54:57], v[158:161], v[166:169], v[54:57]
	global_load_lds_dwordx4 v179, s[100:101]
	v_mfma_f32_16x16x32_bf16 v[50:53], v[162:165], v[166:169], v[50:53]
	ds_read_b128 v[166:169], v202 offset:12288
	s_waitcnt lgkmcnt(1)
	v_mfma_f32_16x16x32_bf16 v[46:49], v[150:153], v[170:173], v[46:49]
	s_add_u32 m0, s42, 0xc000
	v_mfma_f32_16x16x32_bf16 v[42:45], v[154:157], v[170:173], v[42:45]
	global_load_lds_dwordx4 v180, s[100:101]
	v_mfma_f32_16x16x32_bf16 v[38:41], v[158:161], v[170:173], v[38:41]
	s_add_u32 m0, s42, 0xe000
	v_mfma_f32_16x16x32_bf16 v[34:37], v[162:165], v[170:173], v[34:37]
	ds_read_b128 v[170:173], v202 offset:14336
	s_waitcnt lgkmcnt(1)
	v_mfma_f32_16x16x32_bf16 v[30:33], v[150:153], v[166:169], v[30:33]
	global_load_lds_dwordx4 v181, s[100:101]
	v_mfma_f32_16x16x32_bf16 v[26:29], v[154:157], v[166:169], v[26:29]
	v_mfma_f32_16x16x32_bf16 v[22:25], v[158:161], v[166:169], v[22:25]
	v_mfma_f32_16x16x32_bf16 v[18:21], v[162:165], v[166:169], v[18:21]
	s_waitcnt lgkmcnt(0)
	v_mfma_f32_16x16x32_bf16 v[14:17], v[150:153], v[170:173], v[14:17]
	v_mfma_f32_16x16x32_bf16 v[10:13], v[154:157], v[170:173], v[10:13]
	v_mfma_f32_16x16x32_bf16 v[6:9], v[158:161], v[170:173], v[6:9]
	v_mfma_f32_16x16x32_bf16 v[2:5], v[162:165], v[170:173], v[2:5]
	v_add_u32_e32 v162, v190, v144
	ds_read_b128 v[150:153], v162 offset:32768
	ds_read_b128 v[154:157], v162 offset:34816
	ds_read_b128 v[158:161], v162 offset:36864
	ds_read_b128 v[162:165], v162 offset:38912
	v_add_u32_e32 v149, v149, v144
	ds_read_b128 v[166:169], v149
	ds_read_b128 v[170:173], v149 offset:2048
	s_waitcnt lgkmcnt(0)
	v_mfma_f32_16x16x32_bf16 v[126:129], v[150:153], v[166:169], v[126:129]
	s_add_u32 s100, s100, 0x80
	v_mfma_f32_16x16x32_bf16 v[122:125], v[154:157], v[166:169], v[122:125]
	s_addc_u32 s101, s101, 0
	v_mfma_f32_16x16x32_bf16 v[118:121], v[158:161], v[166:169], v[118:121]
	s_add_u32 s16, s16, 0x80
	v_mfma_f32_16x16x32_bf16 v[114:117], v[162:165], v[166:169], v[114:117]
	ds_read_b128 v[166:169], v149 offset:4096
	v_mfma_f32_16x16x32_bf16 v[110:113], v[150:153], v[170:173], v[110:113]
	s_addc_u32 s17, s17, 0
	v_mfma_f32_16x16x32_bf16 v[106:109], v[154:157], v[170:173], v[106:109]
	s_add_i32 s40, s40, 0x10000
	v_mfma_f32_16x16x32_bf16 v[102:105], v[158:161], v[170:173], v[102:105]
	v_mfma_f32_16x16x32_bf16 v[98:101], v[162:165], v[170:173], v[98:101]
	ds_read_b128 v[170:173], v149 offset:6144
	s_waitcnt lgkmcnt(0)
	v_mfma_f32_16x16x32_bf16 v[94:97], v[150:153], v[166:169], v[94:97]
	v_mfma_f32_16x16x32_bf16 v[90:93], v[154:157], v[166:169], v[90:93]
	v_mfma_f32_16x16x32_bf16 v[86:89], v[158:161], v[166:169], v[86:89]
	v_mfma_f32_16x16x32_bf16 v[82:85], v[162:165], v[166:169], v[82:85]
	ds_read_b128 v[166:169], v149 offset:8192
	v_mfma_f32_16x16x32_bf16 v[78:81], v[150:153], v[170:173], v[78:81]
	v_mfma_f32_16x16x32_bf16 v[74:77], v[154:157], v[170:173], v[74:77]
	v_mfma_f32_16x16x32_bf16 v[70:73], v[158:161], v[170:173], v[70:73]
	v_mfma_f32_16x16x32_bf16 v[66:69], v[162:165], v[170:173], v[66:69]
	ds_read_b128 v[170:173], v149 offset:10240
	s_waitcnt lgkmcnt(0)
	v_mfma_f32_16x16x32_bf16 v[62:65], v[150:153], v[166:169], v[62:65]
	v_mfma_f32_16x16x32_bf16 v[58:61], v[154:157], v[166:169], v[58:61]
	v_mfma_f32_16x16x32_bf16 v[54:57], v[158:161], v[166:169], v[54:57]
	v_mfma_f32_16x16x32_bf16 v[50:53], v[162:165], v[166:169], v[50:53]
	ds_read_b128 v[166:169], v149 offset:12288
	v_mfma_f32_16x16x32_bf16 v[46:49], v[150:153], v[170:173], v[46:49]
	v_mfma_f32_16x16x32_bf16 v[42:45], v[154:157], v[170:173], v[42:45]
	v_mfma_f32_16x16x32_bf16 v[38:41], v[158:161], v[170:173], v[38:41]
	v_mfma_f32_16x16x32_bf16 v[34:37], v[162:165], v[170:173], v[34:37]
	ds_read_b128 v[170:173], v149 offset:14336
	s_waitcnt lgkmcnt(0)
	v_mfma_f32_16x16x32_bf16 v[30:33], v[150:153], v[166:169], v[30:33]
	v_mfma_f32_16x16x32_bf16 v[26:29], v[154:157], v[166:169], v[26:29]
	v_mfma_f32_16x16x32_bf16 v[22:25], v[158:161], v[166:169], v[22:25]
	v_mfma_f32_16x16x32_bf16 v[18:21], v[162:165], v[166:169], v[18:21]
	v_mfma_f32_16x16x32_bf16 v[14:17], v[150:153], v[170:173], v[14:17]
	v_mfma_f32_16x16x32_bf16 v[10:13], v[154:157], v[170:173], v[10:13]
	v_mfma_f32_16x16x32_bf16 v[6:9], v[158:161], v[170:173], v[6:9]
	v_mfma_f32_16x16x32_bf16 v[2:5], v[162:165], v[170:173], v[2:5]
	s_cmpk_lg_i32 s16, 0x780
	s_waitcnt vmcnt(0)
	s_barrier
; #define MFMA16(a, b, c) __builtin_amdgcn_mfma_f32_16x16x32_bf16((a), (b), (c), 0, 0, 0)
;     ...
;   for (int kt = 0; kt < nk; ++kt) {
;     const int buf = kt & 1;
;     const char* cA = smem + buf * STAGE + (wm * 32 * MI + r16) * 128;
;     const char* cB = smem + buf * STAGE + 32768 + (wn * 64 + r16) * 128;
; #pragma unroll
;     for (int k2 = 0; k2 < 2; ++k2) {
;       if (k2 == 1 && kt + 1 < nk) STAGE_TILE(buf ^ 1, (kt + 1) * 64)
;       const int po = ((4 * k2 + q4) ^ swz) * 16;
;       bf16x8 bf[4];
; #pragma unroll
;       for (int nt = 0; nt < 4; ++nt) bf[nt] = *(const bf16x8*)(cB + nt * 16 * 128 + po);
;       bf16x8 afc = *(const bf16x8*)(cA + po);
; #pragma unroll
;       for (int a = 0; a < MT; ++a) {
;         bf16x8 afn = afc;
;         if (a + 1 < MT) afn = *(const bf16x8*)(cA + (a + 1) * 16 * 128 + po);
;         __builtin_amdgcn_sched_barrier(0);
; #pragma unroll
;         for (int nt = 0; nt < 4; ++nt) acc[a][nt] = MFMA16(bf[nt], afc, acc[a][nt]);
;         __builtin_amdgcn_sched_barrier(0);
;         afc = afn;
;       }
;     }
	s_cbranch_scc1 .LBB0_75
	s_add_i32 s16, 0, 0x10000
	v_add_u32_e32 v138, s16, v148
	v_readlane_b32 s16, v254, 18
	s_nop 1
	v_add_u32_e32 v139, s16, v147
	v_add_u32_e32 v145, v139, v146
	ds_read_b128 v[130:133], v145
	ds_read_b128 v[134:137], v145 offset:2048
	ds_read_b128 v[148:151], v145 offset:4096
	ds_read_b128 v[152:155], v145 offset:6144
	v_add_u32_e32 v145, v138, v146
	ds_read_b128 v[156:159], v145
	ds_read_b128 v[160:163], v145 offset:2048
	s_waitcnt lgkmcnt(1)
	v_mfma_f32_16x16x32_bf16 v[126:129], v[130:133], v[156:159], v[126:129]
	v_mfma_f32_16x16x32_bf16 v[122:125], v[134:137], v[156:159], v[122:125]
	v_mfma_f32_16x16x32_bf16 v[118:121], v[148:151], v[156:159], v[118:121]
	v_mfma_f32_16x16x32_bf16 v[114:117], v[152:155], v[156:159], v[114:117]
	ds_read_b128 v[156:159], v145 offset:4096
	s_waitcnt lgkmcnt(1)
	v_mfma_f32_16x16x32_bf16 v[110:113], v[130:133], v[160:163], v[110:113]
	v_mfma_f32_16x16x32_bf16 v[106:109], v[134:137], v[160:163], v[106:109]
	v_mfma_f32_16x16x32_bf16 v[102:105], v[148:151], v[160:163], v[102:105]
	v_mfma_f32_16x16x32_bf16 v[98:101], v[152:155], v[160:163], v[98:101]
	ds_read_b128 v[160:163], v145 offset:6144
	s_waitcnt lgkmcnt(1)
	v_mfma_f32_16x16x32_bf16 v[94:97], v[130:133], v[156:159], v[94:97]
	v_mfma_f32_16x16x32_bf16 v[90:93], v[134:137], v[156:159], v[90:93]
	v_mfma_f32_16x16x32_bf16 v[86:89], v[148:151], v[156:159], v[86:89]
	v_mfma_f32_16x16x32_bf16 v[82:85], v[152:155], v[156:159], v[82:85]
	ds_read_b128 v[156:159], v145 offset:8192
	s_waitcnt lgkmcnt(1)
	v_mfma_f32_16x16x32_bf16 v[78:81], v[130:133], v[160:163], v[78:81]
	v_mfma_f32_16x16x32_bf16 v[74:77], v[134:137], v[160:163], v[74:77]
	v_mfma_f32_16x16x32_bf16 v[70:73], v[148:151], v[160:163], v[70:73]
	v_mfma_f32_16x16x32_bf16 v[66:69], v[152:155], v[160:163], v[66:69]
	ds_read_b128 v[160:163], v145 offset:10240
	s_waitcnt lgkmcnt(1)
	v_mfma_f32_16x16x32_bf16 v[62:65], v[130:133], v[156:159], v[62:65]
	v_mfma_f32_16x16x32_bf16 v[58:61], v[134:137], v[156:159], v[58:61]
	v_mfma_f32_16x16x32_bf16 v[54:57], v[148:151], v[156:159], v[54:57]
	v_mfma_f32_16x16x32_bf16 v[50:53], v[152:155], v[156:159], v[50:53]
	ds_read_b128 v[156:159], v145 offset:12288
	s_waitcnt lgkmcnt(1)
	v_mfma_f32_16x16x32_bf16 v[46:49], v[130:133], v[160:163], v[46:49]
	v_mfma_f32_16x16x32_bf16 v[42:45], v[134:137], v[160:163], v[42:45]
	v_mfma_f32_16x16x32_bf16 v[38:41], v[148:151], v[160:163], v[38:41]
	v_mfma_f32_16x16x32_bf16 v[34:37], v[152:155], v[160:163], v[34:37]
	ds_read_b128 v[160:163], v145 offset:14336
	s_waitcnt lgkmcnt(1)
	v_mfma_f32_16x16x32_bf16 v[30:33], v[130:133], v[156:159], v[30:33]
	v_mfma_f32_16x16x32_bf16 v[26:29], v[134:137], v[156:159], v[26:29]
	v_mfma_f32_16x16x32_bf16 v[22:25], v[148:151], v[156:159], v[22:25]
	v_mfma_f32_16x16x32_bf16 v[18:21], v[152:155], v[156:159], v[18:21]
	s_waitcnt lgkmcnt(0)
	v_mfma_f32_16x16x32_bf16 v[14:17], v[130:133], v[160:163], v[14:17]
	v_mfma_f32_16x16x32_bf16 v[10:13], v[134:137], v[160:163], v[10:13]
	v_mfma_f32_16x16x32_bf16 v[6:9], v[148:151], v[160:163], v[6:9]
	v_mfma_f32_16x16x32_bf16 v[2:5], v[152:155], v[160:163], v[2:5]
	v_add_u32_e32 v139, v139, v144
	ds_read_b128 v[130:133], v139
	ds_read_b128 v[134:137], v139 offset:2048
	ds_read_b128 v[146:149], v139 offset:4096
	ds_read_b128 v[150:153], v139 offset:6144
	v_add_u32_e32 v138, v138, v144
	ds_read_b128 v[154:157], v138
	ds_read_b128 v[158:161], v138 offset:2048
	s_waitcnt lgkmcnt(1)
	v_mfma_f32_16x16x32_bf16 v[126:129], v[130:133], v[154:157], v[126:129]
	v_mfma_f32_16x16x32_bf16 v[122:125], v[134:137], v[154:157], v[122:125]
	v_mfma_f32_16x16x32_bf16 v[118:121], v[146:149], v[154:157], v[118:121]
	v_mfma_f32_16x16x32_bf16 v[114:117], v[150:153], v[154:157], v[114:117]
	ds_read_b128 v[154:157], v138 offset:4096
	s_waitcnt lgkmcnt(1)
	v_mfma_f32_16x16x32_bf16 v[162:165], v[130:133], v[158:161], v[110:113]
	v_mfma_f32_16x16x32_bf16 v[166:169], v[134:137], v[158:161], v[106:109]
	v_mfma_f32_16x16x32_bf16 v[102:105], v[146:149], v[158:161], v[102:105]
	v_mfma_f32_16x16x32_bf16 v[98:101], v[150:153], v[158:161], v[98:101]
	s_nop 0
	ds_read_b128 v[106:109], v138 offset:6144
	s_waitcnt lgkmcnt(1)
	v_mfma_f32_16x16x32_bf16 v[94:97], v[130:133], v[154:157], v[94:97]
	v_mfma_f32_16x16x32_bf16 v[90:93], v[134:137], v[154:157], v[90:93]
	v_mfma_f32_16x16x32_bf16 v[86:89], v[146:149], v[154:157], v[86:89]
	v_mfma_f32_16x16x32_bf16 v[82:85], v[150:153], v[154:157], v[82:85]
	ds_read_b128 v[110:113], v138 offset:8192
	s_waitcnt lgkmcnt(1)
	v_mfma_f32_16x16x32_bf16 v[78:81], v[130:133], v[106:109], v[78:81]
	v_mfma_f32_16x16x32_bf16 v[74:77], v[134:137], v[106:109], v[74:77]
	v_mfma_f32_16x16x32_bf16 v[70:73], v[146:149], v[106:109], v[70:73]
	v_mfma_f32_16x16x32_bf16 v[66:69], v[150:153], v[106:109], v[66:69]
	ds_read_b128 v[106:109], v138 offset:10240
	s_waitcnt lgkmcnt(1)
	v_mfma_f32_16x16x32_bf16 v[62:65], v[130:133], v[110:113], v[62:65]
	v_mfma_f32_16x16x32_bf16 v[58:61], v[134:137], v[110:113], v[58:61]
	v_mfma_f32_16x16x32_bf16 v[54:57], v[146:149], v[110:113], v[54:57]
	v_mfma_f32_16x16x32_bf16 v[50:53], v[150:153], v[110:113], v[50:53]
	ds_read_b128 v[110:113], v138 offset:12288
	s_waitcnt lgkmcnt(1)
	v_mfma_f32_16x16x32_bf16 v[46:49], v[130:133], v[106:109], v[46:49]
	v_mfma_f32_16x16x32_bf16 v[42:45], v[134:137], v[106:109], v[42:45]
	v_mfma_f32_16x16x32_bf16 v[38:41], v[146:149], v[106:109], v[38:41]
	v_mfma_f32_16x16x32_bf16 v[34:37], v[150:153], v[106:109], v[34:37]
	ds_read_b128 v[106:109], v138 offset:14336
	s_waitcnt lgkmcnt(1)
; DI unsigned pack2(float a, float b) { hwf2_t f = {a, b}; return __builtin_bit_cast(unsigned, __builtin_convertvector(f, hwbf2_t)); }
; DI float fsigmoid(float x) { return __builtin_amdgcn_rcpf(1.f + __expf(-x)); }
; DI void phase_ffn_up(char* smem, const Params& p, int layer) {
;     ...
;   auto ep = [=](int row, int cb, int q4, const f32x4& c0, const f32x4& c1, const f32x4& c2, const f32x4& c3) {
;     const uint4 o = make_uint4(pack2(c0[0] * fsigmoid(c0[0]) * c0[1], c0[2] * fsigmoid(c0[2]) * c0[3]),
;                                pack2(c1[0] * fsigmoid(c1[0]) * c1[1], c1[2] * fsigmoid(c1[2]) * c1[3]),
;                                pack2(c2[0] * fsigmoid(c2[0]) * c2[1], c2[2] * fsigmoid(c2[2]) * c2[3]),
;                                pack2(c3[0] * fsigmoid(c3[0]) * c3[1], c3[2] * fsigmoid(c3[2]) * c3[3]));
;     *(uint4*)(Hh + (size_t)row * FH + (cb >> 1) + q4 * 8) = o;
	v_mfma_f32_16x16x32_bf16 v[30:33], v[130:133], v[110:113], v[30:33]
	v_mfma_f32_16x16x32_bf16 v[26:29], v[134:137], v[110:113], v[26:29]
	v_mfma_f32_16x16x32_bf16 v[22:25], v[146:149], v[110:113], v[22:25]
	v_mfma_f32_16x16x32_bf16 v[18:21], v[150:153], v[110:113], v[18:21]
	s_waitcnt lgkmcnt(0)
	v_mfma_f32_16x16x32_bf16 v[14:17], v[130:133], v[106:109], v[14:17]
	v_mfma_f32_16x16x32_bf16 v[10:13], v[134:137], v[106:109], v[10:13]
	v_mfma_f32_16x16x32_bf16 v[6:9], v[146:149], v[106:109], v[6:9]
	v_mfma_f32_16x16x32_bf16 v[2:5], v[150:153], v[106:109], v[2:5]
	v_or_b32_e32 v107, s38, v142
	v_lshl_add_u32 v110, v141, 7, v107
	v_mul_f32_e32 v107, 0xbfb8aa3b, v126
	v_mul_f32_e32 v108, 0xbfb8aa3b, v128
	v_exp_f32_e32 v107, v107
	v_exp_f32_e32 v109, v108
	v_lshl_or_b32 v106, v143, 6, s39
	v_ashrrev_i32_e32 v108, 1, v106
	v_add_f32_e32 v106, 1.0, v107
	v_add_f32_e32 v107, 1.0, v109
	v_rcp_f32_e32 v106, v106
	v_rcp_f32_e32 v107, v107
	v_mov_b32_e32 v112, v126
	v_mov_b32_e32 v113, v128
	v_mul_f32_e32 v111, 0xbfb8aa3b, v122
	v_pk_mul_f32 v[106:107], v[112:113], v[106:107]
	v_exp_f32_e32 v111, v111
	v_mul_f32_e32 v112, 0xbfb8aa3b, v124
	v_exp_f32_e32 v113, v112
	v_mov_b32_e32 v128, v127
	v_add_f32_e32 v111, 1.0, v111
	v_rcp_f32_e32 v112, v111
	v_add_f32_e32 v111, 1.0, v113
	v_rcp_f32_e32 v113, v111
	v_pk_mul_f32 v[106:107], v[128:129], v[106:107]
	v_mul_f32_e32 v111, 0xbfb8aa3b, v118
	v_cvt_pk_bf16_f32 v126, v106, v107
	v_mov_b32_e32 v106, v122
	v_mov_b32_e32 v107, v124
	v_pk_mul_f32 v[106:107], v[106:107], v[112:113]
	v_exp_f32_e32 v111, v111
	v_mul_f32_e32 v112, 0xbfb8aa3b, v120
	v_exp_f32_e32 v113, v112
	v_mov_b32_e32 v124, v123
	v_add_f32_e32 v111, 1.0, v111
	v_rcp_f32_e32 v112, v111
	v_add_f32_e32 v111, 1.0, v113
	v_rcp_f32_e32 v113, v111
	v_pk_mul_f32 v[106:107], v[124:125], v[106:107]
	v_mul_f32_e32 v111, 0xbfb8aa3b, v114
	v_cvt_pk_bf16_f32 v127, v106, v107
	v_mov_b32_e32 v106, v118
	v_mov_b32_e32 v107, v120
	v_pk_mul_f32 v[106:107], v[106:107], v[112:113]
	v_exp_f32_e32 v111, v111
	v_mul_f32_e32 v112, 0xbfb8aa3b, v116
	v_exp_f32_e32 v113, v112
	v_mov_b32_e32 v120, v119
	v_add_f32_e32 v111, 1.0, v111
	v_rcp_f32_e32 v112, v111
	v_add_f32_e32 v111, 1.0, v113
	v_rcp_f32_e32 v113, v111
	v_pk_mul_f32 v[106:107], v[120:121], v[106:107]
	v_readlane_b32 s52, v253, 40
	v_cvt_pk_bf16_f32 v128, v106, v107
	v_mov_b32_e32 v106, v114
	v_mov_b32_e32 v107, v116
	v_pk_mul_f32 v[106:107], v[106:107], v[112:113]
	v_mov_b32_e32 v116, v115
	v_mul_f32_e32 v111, 0xbfb8aa3b, v162
	v_pk_mul_f32 v[106:107], v[116:117], v[106:107]
	v_readlane_b32 s54, v253, 42
	v_readlane_b32 s55, v253, 43
	v_exp_f32_e32 v111, v111
	v_mul_f32_e32 v114, 0xbfb8aa3b, v164
	v_ashrrev_i32_e32 v109, 31, v108
	v_cvt_pk_bf16_f32 v129, v106, v107
	v_mov_b64_e32 v[106:107], s[54:55]
	s_movk_i32 s38, 0x1600
	v_exp_f32_e32 v114, v114
	v_mad_i64_i32 v[112:113], s[16:17], v110, s38, v[106:107]
	v_lshlrev_b64 v[108:109], 1, v[108:109]
	v_lshl_add_u64 v[112:113], v[112:113], 0, v[108:109]
	v_lshlrev_b32_e32 v190, 4, v140
	v_lshl_add_u64 v[112:113], v[112:113], 0, v[190:191]
	v_add_f32_e32 v111, 1.0, v111
	s_waitcnt vmcnt(0)
	s_barrier
	global_store_dwordx4 v[112:113], v[126:129], off
	v_rcp_f32_e32 v112, v111
	v_add_f32_e32 v111, 1.0, v114
	v_rcp_f32_e32 v113, v111
	v_mov_b32_e32 v114, v162
	v_mov_b32_e32 v115, v164
	v_mov_b32_e32 v164, v163
	v_pk_mul_f32 v[112:113], v[114:115], v[112:113]
	v_mul_f32_e32 v114, 0xbfb8aa3b, v166
	v_mul_f32_e32 v115, 0xbfb8aa3b, v168
	v_exp_f32_e32 v114, v114
	v_exp_f32_e32 v115, v115
	v_pk_mul_f32 v[112:113], v[164:165], v[112:113]
	v_mov_b32_e32 v116, v166
	v_add_f32_e32 v114, 1.0, v114
	v_add_f32_e32 v115, 1.0, v115
	v_rcp_f32_e32 v114, v114
	v_rcp_f32_e32 v115, v115
	v_cvt_pk_bf16_f32 v112, v112, v113
	v_mov_b32_e32 v117, v168
	v_mul_f32_e32 v113, 0xbfb8aa3b, v102
	v_pk_mul_f32 v[114:115], v[116:117], v[114:115]
	v_exp_f32_e32 v113, v113
	v_mul_f32_e32 v116, 0xbfb8aa3b, v104
	v_exp_f32_e32 v117, v116
	v_mov_b32_e32 v168, v167
	v_add_f32_e32 v113, 1.0, v113
	v_rcp_f32_e32 v116, v113
	v_add_f32_e32 v113, 1.0, v117
	v_rcp_f32_e32 v117, v113
	v_pk_mul_f32 v[114:115], v[168:169], v[114:115]
	v_or_b32_e32 v111, 16, v110
	v_cvt_pk_bf16_f32 v113, v114, v115
	v_mov_b32_e32 v114, v102
	v_mov_b32_e32 v115, v104
	v_mul_f32_e32 v102, 0xbfb8aa3b, v98
	v_pk_mul_f32 v[114:115], v[114:115], v[116:117]
	v_exp_f32_e32 v116, v102
	v_mul_f32_e32 v102, 0xbfb8aa3b, v100
	v_exp_f32_e32 v117, v102
	v_mov_b32_e32 v104, v103
	v_pk_mul_f32 v[102:103], v[104:105], v[114:115]
	v_add_f32_e32 v104, 1.0, v116
	v_add_f32_e32 v105, 1.0, v117
	v_rcp_f32_e32 v104, v104
	v_rcp_f32_e32 v105, v105
	v_cvt_pk_bf16_f32 v114, v102, v103
	v_mov_b32_e32 v102, v98
	v_mov_b32_e32 v103, v100
	v_pk_mul_f32 v[102:103], v[102:103], v[104:105]
	v_mov_b32_e32 v100, v99
	v_pk_mul_f32 v[98:99], v[100:101], v[102:103]
	v_mul_f32_e32 v100, 0xbfb8aa3b, v94
	v_mul_f32_e32 v101, 0xbfb8aa3b, v96
	v_exp_f32_e32 v100, v100
	v_exp_f32_e32 v101, v101
	v_cvt_pk_bf16_f32 v115, v98, v99
	v_mad_i64_i32 v[98:99], s[16:17], v111, s38, v[106:107]
	v_lshl_add_u64 v[98:99], v[98:99], 0, v[108:109]
	v_lshl_add_u64 v[98:99], v[98:99], 0, v[190:191]
	global_store_dwordx4 v[98:99], v[112:115], off
	v_add_f32_e32 v98, 1.0, v100
	v_add_f32_e32 v99, 1.0, v101
	v_rcp_f32_e32 v98, v98
	v_rcp_f32_e32 v99, v99
	v_mov_b32_e32 v100, v94
	v_mov_b32_e32 v101, v96
	v_mul_f32_e32 v94, 0xbfb8aa3b, v90
	v_pk_mul_f32 v[98:99], v[100:101], v[98:99]
	v_exp_f32_e32 v100, v94
	v_mul_f32_e32 v94, 0xbfb8aa3b, v92
	v_exp_f32_e32 v101, v94
	v_mov_b32_e32 v96, v95
	v_pk_mul_f32 v[94:95], v[96:97], v[98:99]
	v_add_f32_e32 v96, 1.0, v100
	v_add_f32_e32 v97, 1.0, v101
; DI unsigned pack2(float a, float b) { hwf2_t f = {a, b}; return __builtin_bit_cast(unsigned, __builtin_convertvector(f, hwbf2_t)); }
; DI float fsigmoid(float x) { return __builtin_amdgcn_rcpf(1.f + __expf(-x)); }
; DI void phase_ffn_up(char* smem, const Params& p, int layer) {
;     ...
;   auto ep = [=](int row, int cb, int q4, const f32x4& c0, const f32x4& c1, const f32x4& c2, const f32x4& c3) {
;     const uint4 o = make_uint4(pack2(c0[0] * fsigmoid(c0[0]) * c0[1], c0[2] * fsigmoid(c0[2]) * c0[3]),
;                                pack2(c1[0] * fsigmoid(c1[0]) * c1[1], c1[2] * fsigmoid(c1[2]) * c1[3]),
;                                pack2(c2[0] * fsigmoid(c2[0]) * c2[1], c2[2] * fsigmoid(c2[2]) * c2[3]),
;                                pack2(c3[0] * fsigmoid(c3[0]) * c3[1], c3[2] * fsigmoid(c3[2]) * c3[3]));
;     *(uint4*)(Hh + (size_t)row * FH + (cb >> 1) + q4 * 8) = o;
	v_rcp_f32_e32 v96, v96
	v_rcp_f32_e32 v97, v97
	v_mov_b32_e32 v98, v90
	v_mul_f32_e32 v90, 0xbfb8aa3b, v86
	v_cvt_pk_bf16_f32 v94, v94, v95
	v_mov_b32_e32 v99, v92
	v_exp_f32_e32 v95, v90
	v_mul_f32_e32 v90, 0xbfb8aa3b, v88
	v_pk_mul_f32 v[96:97], v[98:99], v[96:97]
	v_exp_f32_e32 v98, v90
	v_mov_b32_e32 v92, v91
	v_pk_mul_f32 v[90:91], v[92:93], v[96:97]
	v_add_f32_e32 v92, 1.0, v95
	v_add_f32_e32 v93, 1.0, v98
	v_rcp_f32_e32 v92, v92
	v_rcp_f32_e32 v93, v93
	v_cvt_pk_bf16_f32 v95, v90, v91
	v_mov_b32_e32 v90, v86
	v_mov_b32_e32 v91, v88
	v_mul_f32_e32 v86, 0xbfb8aa3b, v82
	v_pk_mul_f32 v[90:91], v[90:91], v[92:93]
	v_exp_f32_e32 v92, v86
	v_mul_f32_e32 v86, 0xbfb8aa3b, v84
	v_exp_f32_e32 v93, v86
	v_mov_b32_e32 v88, v87
	v_pk_mul_f32 v[86:87], v[88:89], v[90:91]
	v_add_f32_e32 v88, 1.0, v92
	v_add_f32_e32 v89, 1.0, v93
	v_rcp_f32_e32 v88, v88
	v_rcp_f32_e32 v89, v89
	v_cvt_pk_bf16_f32 v96, v86, v87
	v_mov_b32_e32 v86, v82
	v_mov_b32_e32 v87, v84
	v_pk_mul_f32 v[86:87], v[86:87], v[88:89]
	v_mov_b32_e32 v84, v83
	v_pk_mul_f32 v[82:83], v[84:85], v[86:87]
	v_mul_f32_e32 v84, 0xbfb8aa3b, v78
	v_mul_f32_e32 v85, 0xbfb8aa3b, v80
	v_or_b32_e32 v102, 32, v110
	v_exp_f32_e32 v84, v84
	v_exp_f32_e32 v85, v85
	v_cvt_pk_bf16_f32 v97, v82, v83
	v_mad_i64_i32 v[82:83], s[16:17], v102, s38, v[106:107]
	v_lshl_add_u64 v[82:83], v[82:83], 0, v[108:109]
	v_lshl_add_u64 v[82:83], v[82:83], 0, v[190:191]
	global_store_dwordx4 v[82:83], v[94:97], off
	v_add_f32_e32 v82, 1.0, v84
	v_add_f32_e32 v83, 1.0, v85
	v_rcp_f32_e32 v82, v82
	v_rcp_f32_e32 v83, v83
	v_mov_b32_e32 v84, v78
	v_mov_b32_e32 v85, v80
	v_mul_f32_e32 v78, 0xbfb8aa3b, v74
	v_pk_mul_f32 v[82:83], v[84:85], v[82:83]
	v_exp_f32_e32 v84, v78
	v_mul_f32_e32 v78, 0xbfb8aa3b, v76
	v_exp_f32_e32 v85, v78
	v_mov_b32_e32 v80, v79
	v_pk_mul_f32 v[78:79], v[80:81], v[82:83]
	v_add_f32_e32 v80, 1.0, v84
	v_add_f32_e32 v81, 1.0, v85
	v_rcp_f32_e32 v80, v80
	v_rcp_f32_e32 v81, v81
	v_mov_b32_e32 v82, v74
	v_mul_f32_e32 v74, 0xbfb8aa3b, v70
	v_cvt_pk_bf16_f32 v78, v78, v79
	v_mov_b32_e32 v83, v76
	v_exp_f32_e32 v79, v74
	v_mul_f32_e32 v74, 0xbfb8aa3b, v72
	v_pk_mul_f32 v[80:81], v[82:83], v[80:81]
	v_exp_f32_e32 v82, v74
	v_mov_b32_e32 v76, v75
	v_pk_mul_f32 v[74:75], v[76:77], v[80:81]
	v_add_f32_e32 v76, 1.0, v79
	v_add_f32_e32 v77, 1.0, v82
	v_rcp_f32_e32 v76, v76
	v_rcp_f32_e32 v77, v77
	v_cvt_pk_bf16_f32 v79, v74, v75
	v_mov_b32_e32 v74, v70
	v_mov_b32_e32 v75, v72
	v_mul_f32_e32 v70, 0xbfb8aa3b, v66
	v_pk_mul_f32 v[74:75], v[74:75], v[76:77]
	v_exp_f32_e32 v76, v70
	v_mul_f32_e32 v70, 0xbfb8aa3b, v68
	v_exp_f32_e32 v77, v70
	v_mov_b32_e32 v72, v71
	v_pk_mul_f32 v[70:71], v[72:73], v[74:75]
	v_add_f32_e32 v72, 1.0, v76
	v_add_f32_e32 v73, 1.0, v77
	v_rcp_f32_e32 v72, v72
	v_rcp_f32_e32 v73, v73
	v_cvt_pk_bf16_f32 v80, v70, v71
	v_mov_b32_e32 v70, v66
	v_mov_b32_e32 v71, v68
	v_pk_mul_f32 v[70:71], v[70:71], v[72:73]
	v_mov_b32_e32 v68, v67
	v_pk_mul_f32 v[66:67], v[68:69], v[70:71]
	v_mul_f32_e32 v68, 0xbfb8aa3b, v62
	v_mul_f32_e32 v69, 0xbfb8aa3b, v64
	v_or_b32_e32 v86, 48, v110
	v_exp_f32_e32 v68, v68
	v_exp_f32_e32 v69, v69
	v_cvt_pk_bf16_f32 v81, v66, v67
	v_mad_i64_i32 v[66:67], s[16:17], v86, s38, v[106:107]
	v_lshl_add_u64 v[66:67], v[66:67], 0, v[108:109]
	v_lshl_add_u64 v[66:67], v[66:67], 0, v[190:191]
	global_store_dwordx4 v[66:67], v[78:81], off
	v_add_f32_e32 v66, 1.0, v68
	v_add_f32_e32 v67, 1.0, v69
	v_rcp_f32_e32 v66, v66
	v_rcp_f32_e32 v67, v67
	v_mov_b32_e32 v68, v62
	v_mov_b32_e32 v69, v64
	v_mul_f32_e32 v62, 0xbfb8aa3b, v58
	v_pk_mul_f32 v[66:67], v[68:69], v[66:67]
	v_exp_f32_e32 v68, v62
	v_mul_f32_e32 v62, 0xbfb8aa3b, v60
	v_exp_f32_e32 v69, v62
	v_mov_b32_e32 v64, v63
	v_pk_mul_f32 v[62:63], v[64:65], v[66:67]
	v_add_f32_e32 v64, 1.0, v68
	v_add_f32_e32 v65, 1.0, v69
	v_rcp_f32_e32 v64, v64
	v_rcp_f32_e32 v65, v65
	v_mov_b32_e32 v66, v58
	v_mul_f32_e32 v58, 0xbfb8aa3b, v54
	v_cvt_pk_bf16_f32 v62, v62, v63
	v_mov_b32_e32 v67, v60
	v_exp_f32_e32 v63, v58
	v_mul_f32_e32 v58, 0xbfb8aa3b, v56
	v_pk_mul_f32 v[64:65], v[66:67], v[64:65]
	v_exp_f32_e32 v66, v58
	v_mov_b32_e32 v60, v59
	v_pk_mul_f32 v[58:59], v[60:61], v[64:65]
	v_add_f32_e32 v60, 1.0, v63
	v_add_f32_e32 v61, 1.0, v66
	v_rcp_f32_e32 v60, v60
	v_rcp_f32_e32 v61, v61
	v_cvt_pk_bf16_f32 v63, v58, v59
	v_mov_b32_e32 v58, v54
	v_mov_b32_e32 v59, v56
	v_mul_f32_e32 v54, 0xbfb8aa3b, v50
	v_pk_mul_f32 v[58:59], v[58:59], v[60:61]
	v_exp_f32_e32 v60, v54
	v_mul_f32_e32 v54, 0xbfb8aa3b, v52
	v_exp_f32_e32 v61, v54
	v_mov_b32_e32 v56, v55
	v_pk_mul_f32 v[54:55], v[56:57], v[58:59]
	v_add_f32_e32 v56, 1.0, v60
	v_add_f32_e32 v57, 1.0, v61
	v_rcp_f32_e32 v56, v56
	v_rcp_f32_e32 v57, v57
	v_cvt_pk_bf16_f32 v64, v54, v55
	v_mov_b32_e32 v54, v50
	v_mov_b32_e32 v55, v52
	v_pk_mul_f32 v[54:55], v[54:55], v[56:57]
	v_mov_b32_e32 v52, v51
	v_pk_mul_f32 v[50:51], v[52:53], v[54:55]
	v_mul_f32_e32 v52, 0xbfb8aa3b, v46
	v_mul_f32_e32 v53, 0xbfb8aa3b, v48
	v_or_b32_e32 v70, 64, v110
	v_exp_f32_e32 v52, v52
	v_exp_f32_e32 v53, v53
	v_cvt_pk_bf16_f32 v65, v50, v51
	v_mad_i64_i32 v[50:51], s[16:17], v70, s38, v[106:107]
	v_lshl_add_u64 v[50:51], v[50:51], 0, v[108:109]
	v_lshl_add_u64 v[50:51], v[50:51], 0, v[190:191]
	global_store_dwordx4 v[50:51], v[62:65], off
	v_add_f32_e32 v50, 1.0, v52
	v_add_f32_e32 v51, 1.0, v53
	v_rcp_f32_e32 v50, v50
	v_rcp_f32_e32 v51, v51
	v_mov_b32_e32 v52, v46
	v_mov_b32_e32 v53, v48
	v_mul_f32_e32 v46, 0xbfb8aa3b, v42
	v_pk_mul_f32 v[50:51], v[52:53], v[50:51]
	v_exp_f32_e32 v52, v46
	v_mul_f32_e32 v46, 0xbfb8aa3b, v44
	v_exp_f32_e32 v53, v46
	v_mov_b32_e32 v48, v47
	v_pk_mul_f32 v[46:47], v[48:49], v[50:51]
; DI unsigned pack2(float a, float b) { hwf2_t f = {a, b}; return __builtin_bit_cast(unsigned, __builtin_convertvector(f, hwbf2_t)); }
; DI float fsigmoid(float x) { return __builtin_amdgcn_rcpf(1.f + __expf(-x)); }
; template <int TMI, class F>
; DI void for_tiles_xcd(int MT, int NT, const F& f) {
;     ...
;     for (int c = x; c * 32 < total_full; c += 8)
;       for (int kk = slot; kk < 32; kk += nslots) {
;         const int L = c * 32 + kk;
;         if (L >= total_full) break;
;         int mt, nt; decode(L, mt, nt);
;         f(mt * 256, nt, std::integral_constant<int, 4>{});
; DI void phase_ffn_up(char* smem, const Params& p, int layer) {
;     ...
;   auto ep = [=](int row, int cb, int q4, const f32x4& c0, const f32x4& c1, const f32x4& c2, const f32x4& c3) {
;     const uint4 o = make_uint4(pack2(c0[0] * fsigmoid(c0[0]) * c0[1], c0[2] * fsigmoid(c0[2]) * c0[3]),
;                                pack2(c1[0] * fsigmoid(c1[0]) * c1[1], c1[2] * fsigmoid(c1[2]) * c1[3]),
;                                pack2(c2[0] * fsigmoid(c2[0]) * c2[1], c2[2] * fsigmoid(c2[2]) * c2[3]),
;                                pack2(c3[0] * fsigmoid(c3[0]) * c3[1], c3[2] * fsigmoid(c3[2]) * c3[3]));
;     *(uint4*)(Hh + (size_t)row * FH + (cb >> 1) + q4 * 8) = o;
	v_add_f32_e32 v48, 1.0, v52
	v_add_f32_e32 v49, 1.0, v53
	v_rcp_f32_e32 v48, v48
	v_rcp_f32_e32 v49, v49
	v_mov_b32_e32 v50, v42
	v_mul_f32_e32 v42, 0xbfb8aa3b, v38
	v_cvt_pk_bf16_f32 v46, v46, v47
	v_mov_b32_e32 v51, v44
	v_exp_f32_e32 v47, v42
	v_mul_f32_e32 v42, 0xbfb8aa3b, v40
	v_pk_mul_f32 v[48:49], v[50:51], v[48:49]
	v_exp_f32_e32 v50, v42
	v_mov_b32_e32 v44, v43
	v_pk_mul_f32 v[42:43], v[44:45], v[48:49]
	v_add_f32_e32 v44, 1.0, v47
	v_add_f32_e32 v45, 1.0, v50
	v_rcp_f32_e32 v44, v44
	v_rcp_f32_e32 v45, v45
	v_cvt_pk_bf16_f32 v47, v42, v43
	v_mov_b32_e32 v42, v38
	v_mov_b32_e32 v43, v40
	v_mul_f32_e32 v38, 0xbfb8aa3b, v34
	v_pk_mul_f32 v[42:43], v[42:43], v[44:45]
	v_exp_f32_e32 v44, v38
	v_mul_f32_e32 v38, 0xbfb8aa3b, v36
	v_exp_f32_e32 v45, v38
	v_mov_b32_e32 v40, v39
	v_pk_mul_f32 v[38:39], v[40:41], v[42:43]
	v_add_f32_e32 v40, 1.0, v44
	v_add_f32_e32 v41, 1.0, v45
	v_rcp_f32_e32 v40, v40
	v_rcp_f32_e32 v41, v41
	v_cvt_pk_bf16_f32 v48, v38, v39
	v_mov_b32_e32 v38, v34
	v_mov_b32_e32 v39, v36
	v_pk_mul_f32 v[38:39], v[38:39], v[40:41]
	v_mov_b32_e32 v36, v35
	v_pk_mul_f32 v[34:35], v[36:37], v[38:39]
	v_mul_f32_e32 v36, 0xbfb8aa3b, v30
	v_mul_f32_e32 v37, 0xbfb8aa3b, v32
	v_or_b32_e32 v54, 0x50, v110
	v_exp_f32_e32 v36, v36
	v_exp_f32_e32 v37, v37
	v_cvt_pk_bf16_f32 v49, v34, v35
	v_mad_i64_i32 v[34:35], s[16:17], v54, s38, v[106:107]
	v_lshl_add_u64 v[34:35], v[34:35], 0, v[108:109]
	v_lshl_add_u64 v[34:35], v[34:35], 0, v[190:191]
	global_store_dwordx4 v[34:35], v[46:49], off
	v_add_f32_e32 v34, 1.0, v36
	v_add_f32_e32 v35, 1.0, v37
	v_rcp_f32_e32 v34, v34
	v_rcp_f32_e32 v35, v35
	v_mov_b32_e32 v36, v30
	v_mov_b32_e32 v37, v32
	v_mul_f32_e32 v30, 0xbfb8aa3b, v26
	v_pk_mul_f32 v[34:35], v[36:37], v[34:35]
	v_exp_f32_e32 v36, v30
	v_mul_f32_e32 v30, 0xbfb8aa3b, v28
	v_exp_f32_e32 v37, v30
	v_mov_b32_e32 v32, v31
	v_pk_mul_f32 v[30:31], v[32:33], v[34:35]
	v_add_f32_e32 v32, 1.0, v36
	v_add_f32_e32 v33, 1.0, v37
	v_rcp_f32_e32 v32, v32
	v_rcp_f32_e32 v33, v33
	v_mov_b32_e32 v34, v26
	v_mul_f32_e32 v26, 0xbfb8aa3b, v22
	v_cvt_pk_bf16_f32 v30, v30, v31
	v_mov_b32_e32 v35, v28
	v_exp_f32_e32 v31, v26
	v_mul_f32_e32 v26, 0xbfb8aa3b, v24
	v_pk_mul_f32 v[32:33], v[34:35], v[32:33]
	v_exp_f32_e32 v34, v26
	v_mov_b32_e32 v28, v27
	v_pk_mul_f32 v[26:27], v[28:29], v[32:33]
	v_add_f32_e32 v28, 1.0, v31
	v_add_f32_e32 v29, 1.0, v34
	v_rcp_f32_e32 v28, v28
	v_rcp_f32_e32 v29, v29
	v_cvt_pk_bf16_f32 v31, v26, v27
	v_mov_b32_e32 v26, v22
	v_mov_b32_e32 v27, v24
	v_mul_f32_e32 v22, 0xbfb8aa3b, v18
	v_pk_mul_f32 v[26:27], v[26:27], v[28:29]
	v_exp_f32_e32 v28, v22
	v_mul_f32_e32 v22, 0xbfb8aa3b, v20
	v_exp_f32_e32 v29, v22
	v_mov_b32_e32 v24, v23
	v_pk_mul_f32 v[22:23], v[24:25], v[26:27]
	v_add_f32_e32 v24, 1.0, v28
	v_add_f32_e32 v25, 1.0, v29
	v_rcp_f32_e32 v24, v24
	v_rcp_f32_e32 v25, v25
	v_cvt_pk_bf16_f32 v32, v22, v23
	v_mov_b32_e32 v22, v18
	v_mov_b32_e32 v23, v20
	v_pk_mul_f32 v[22:23], v[22:23], v[24:25]
	v_mov_b32_e32 v20, v19
	v_pk_mul_f32 v[18:19], v[20:21], v[22:23]
	v_mul_f32_e32 v20, 0xbfb8aa3b, v14
	v_mul_f32_e32 v21, 0xbfb8aa3b, v16
	v_or_b32_e32 v38, 0x60, v110
	v_exp_f32_e32 v20, v20
	v_exp_f32_e32 v21, v21
	v_cvt_pk_bf16_f32 v33, v18, v19
	v_mad_i64_i32 v[18:19], s[16:17], v38, s38, v[106:107]
	v_lshl_add_u64 v[18:19], v[18:19], 0, v[108:109]
	v_lshl_add_u64 v[18:19], v[18:19], 0, v[190:191]
	global_store_dwordx4 v[18:19], v[30:33], off
	v_add_f32_e32 v18, 1.0, v20
	v_add_f32_e32 v19, 1.0, v21
	v_rcp_f32_e32 v18, v18
	v_rcp_f32_e32 v19, v19
	v_mov_b32_e32 v20, v14
	v_mov_b32_e32 v21, v16
	v_mul_f32_e32 v14, 0xbfb8aa3b, v10
	v_pk_mul_f32 v[18:19], v[20:21], v[18:19]
	v_exp_f32_e32 v20, v14
	v_mul_f32_e32 v14, 0xbfb8aa3b, v12
	v_exp_f32_e32 v21, v14
	v_mov_b32_e32 v16, v15
	v_pk_mul_f32 v[14:15], v[16:17], v[18:19]
	v_add_f32_e32 v16, 1.0, v20
	v_add_f32_e32 v17, 1.0, v21
	v_rcp_f32_e32 v16, v16
	v_rcp_f32_e32 v17, v17
	v_mov_b32_e32 v18, v10
	v_mul_f32_e32 v10, 0xbfb8aa3b, v6
	v_cvt_pk_bf16_f32 v14, v14, v15
	v_mov_b32_e32 v19, v12
	v_exp_f32_e32 v15, v10
	v_mul_f32_e32 v10, 0xbfb8aa3b, v8
	v_pk_mul_f32 v[16:17], v[18:19], v[16:17]
	v_exp_f32_e32 v18, v10
	v_mov_b32_e32 v12, v11
	v_pk_mul_f32 v[10:11], v[12:13], v[16:17]
	v_add_f32_e32 v12, 1.0, v15
	v_add_f32_e32 v13, 1.0, v18
	v_rcp_f32_e32 v12, v12
	v_rcp_f32_e32 v13, v13
	v_cvt_pk_bf16_f32 v15, v10, v11
	v_mov_b32_e32 v10, v6
	v_mov_b32_e32 v11, v8
	v_mul_f32_e32 v6, 0xbfb8aa3b, v2
	v_pk_mul_f32 v[10:11], v[10:11], v[12:13]
	v_exp_f32_e32 v12, v6
	v_mul_f32_e32 v6, 0xbfb8aa3b, v4
	v_exp_f32_e32 v13, v6
	v_mov_b32_e32 v8, v7
	v_pk_mul_f32 v[6:7], v[8:9], v[10:11]
	v_add_f32_e32 v8, 1.0, v12
	v_add_f32_e32 v9, 1.0, v13
	v_rcp_f32_e32 v8, v8
	v_rcp_f32_e32 v9, v9
	v_cvt_pk_bf16_f32 v16, v6, v7
	v_mov_b32_e32 v6, v2
	v_mov_b32_e32 v7, v4
	v_pk_mul_f32 v[6:7], v[6:7], v[8:9]
	v_mov_b32_e32 v4, v3
	v_or_b32_e32 v22, 0x70, v110
	v_pk_mul_f32 v[2:3], v[4:5], v[6:7]
	s_add_i32 s37, s37, s30
	v_cvt_pk_bf16_f32 v17, v2, v3
	v_mad_i64_i32 v[2:3], s[16:17], v22, s38, v[106:107]
	v_lshl_add_u64 v[2:3], v[2:3], 0, v[108:109]
	s_cmp_gt_i32 s37, 31
	v_lshl_add_u64 v[2:3], v[2:3], 0, v[190:191]
	s_cselect_b64 s[16:17], -1, 0
	v_readlane_b32 s53, v253, 41
	v_readlane_b32 s56, v253, 44
	v_readlane_b32 s57, v253, 45
	v_readlane_b32 s58, v253, 46
	v_readlane_b32 s59, v253, 47
	v_readlane_b32 s60, v253, 48
	v_readlane_b32 s61, v253, 49
	v_readlane_b32 s62, v253, 50
	v_readlane_b32 s63, v253, 51
	v_readlane_b32 s64, v253, 52
	v_readlane_b32 s65, v253, 53
	v_readlane_b32 s66, v253, 54
	v_readlane_b32 s67, v253, 55
	global_store_dwordx4 v[2:3], v[14:17], off
	s_branch .LBB0_68

; #define MFMA16(a, b, c) __builtin_amdgcn_mfma_f32_16x16x32_bf16((a), (b), (c), 0, 0, 0)
;     ...
;   for (int kt = 0; kt < nk; ++kt) {
;     const int buf = kt & 1;
;     const char* cA = smem + buf * STAGE + (wm * 32 * MI + r16) * 128;
;     const char* cB = smem + buf * STAGE + 32768 + (wn * 64 + r16) * 128;
; #pragma unroll
;     for (int k2 = 0; k2 < 2; ++k2) {
;       if (k2 == 1 && kt + 1 < nk) STAGE_TILE(buf ^ 1, (kt + 1) * 64)
;       const int po = ((4 * k2 + q4) ^ swz) * 16;
;       bf16x8 bf[4];
; #pragma unroll
;       for (int nt = 0; nt < 4; ++nt) bf[nt] = *(const bf16x8*)(cB + nt * 16 * 128 + po);
;       bf16x8 afc = *(const bf16x8*)(cA + po);
; #pragma unroll
;       for (int a = 0; a < MT; ++a) {
;         bf16x8 afn = afc;
;         if (a + 1 < MT) afn = *(const bf16x8*)(cA + (a + 1) * 16 * 128 + po);
;         __builtin_amdgcn_sched_barrier(0);
; #pragma unroll
;         for (int nt = 0; nt < 4; ++nt) acc[a][nt] = MFMA16(bf[nt], afc, acc[a][nt]);
;         __builtin_amdgcn_sched_barrier(0);
;         afc = afn;
;       }
;     }
;     asm volatile("s_waitcnt vmcnt(0)" ::: "memory");
;     __syncthreads();
;   }
.LBB0_107:
	s_and_b32 s46, s45, 0x10000
	s_add_i32 s47, s46, 0
	s_xor_b32 s46, s46, 0x10000
	v_add_u32_e32 v174, s47, v147
	v_add_u32_e32 v162, v174, v146
	v_add_u32_e32 v149, s47, v148
	ds_read_b128 v[150:153], v162 offset:32768
	ds_read_b128 v[154:157], v162 offset:34816
	ds_read_b128 v[158:161], v162 offset:36864
	ds_read_b128 v[162:165], v162 offset:38912
	v_add_u32_e32 v175, v149, v146
	ds_read_b128 v[166:169], v175
	ds_read_b128 v[170:173], v175 offset:2048
	s_waitcnt lgkmcnt(1)
	v_mfma_f32_16x16x32_bf16 v[126:129], v[150:153], v[166:169], v[126:129]
	v_readfirstlane_b32 s47, v145
	v_mfma_f32_16x16x32_bf16 v[122:125], v[154:157], v[166:169], v[122:125]
	s_nop 0
	v_mfma_f32_16x16x32_bf16 v[118:121], v[158:161], v[166:169], v[118:121]
	s_add_u32 s47, s47, s46
	v_mfma_f32_16x16x32_bf16 v[114:117], v[162:165], v[166:169], v[114:117]
	ds_read_b128 v[166:169], v175 offset:4096
	s_waitcnt lgkmcnt(1)
	v_mfma_f32_16x16x32_bf16 v[110:113], v[150:153], v[170:173], v[110:113]
	s_add_u32 m0, s47, 0x0
	v_mfma_f32_16x16x32_bf16 v[106:109], v[154:157], v[170:173], v[106:109]
	global_load_lds_dwordx4 v176, s[100:101]
	v_mfma_f32_16x16x32_bf16 v[102:105], v[158:161], v[170:173], v[102:105]
	s_add_u32 m0, s47, 0x2000
	v_mfma_f32_16x16x32_bf16 v[98:101], v[162:165], v[170:173], v[98:101]
	ds_read_b128 v[170:173], v175 offset:6144
	s_waitcnt lgkmcnt(1)
	v_mfma_f32_16x16x32_bf16 v[94:97], v[150:153], v[166:169], v[94:97]
	global_load_lds_dwordx4 v177, s[100:101]
	v_mfma_f32_16x16x32_bf16 v[90:93], v[154:157], v[166:169], v[90:93]
	s_add_u32 m0, s47, 0x4000
	v_mfma_f32_16x16x32_bf16 v[86:89], v[158:161], v[166:169], v[86:89]
	global_load_lds_dwordx4 v178, s[100:101]
	v_mfma_f32_16x16x32_bf16 v[82:85], v[162:165], v[166:169], v[82:85]
	ds_read_b128 v[166:169], v175 offset:8192
	s_waitcnt lgkmcnt(1)
	v_mfma_f32_16x16x32_bf16 v[78:81], v[150:153], v[170:173], v[78:81]
	s_add_u32 m0, s47, 0x6000
	v_mfma_f32_16x16x32_bf16 v[74:77], v[154:157], v[170:173], v[74:77]
	global_load_lds_dwordx4 v179, s[100:101]
	v_mfma_f32_16x16x32_bf16 v[70:73], v[158:161], v[170:173], v[70:73]
	s_add_u32 m0, s47, 0x8000
	v_mfma_f32_16x16x32_bf16 v[66:69], v[162:165], v[170:173], v[66:69]
	ds_read_b128 v[170:173], v175 offset:10240
	s_waitcnt lgkmcnt(1)
	v_mfma_f32_16x16x32_bf16 v[62:65], v[150:153], v[166:169], v[62:65]
	global_load_lds_dwordx4 v180, s[100:101]
	v_mfma_f32_16x16x32_bf16 v[58:61], v[154:157], v[166:169], v[58:61]
	s_add_u32 m0, s47, 0xa000
	v_mfma_f32_16x16x32_bf16 v[54:57], v[158:161], v[166:169], v[54:57]
	global_load_lds_dwordx4 v181, s[100:101]
	v_mfma_f32_16x16x32_bf16 v[50:53], v[162:165], v[166:169], v[50:53]
	ds_read_b128 v[166:169], v175 offset:12288
	s_waitcnt lgkmcnt(1)
	v_mfma_f32_16x16x32_bf16 v[46:49], v[150:153], v[170:173], v[46:49]
	s_add_u32 m0, s47, 0xc000
	v_mfma_f32_16x16x32_bf16 v[42:45], v[154:157], v[170:173], v[42:45]
	global_load_lds_dwordx4 v182, s[100:101]
	v_mfma_f32_16x16x32_bf16 v[38:41], v[158:161], v[170:173], v[38:41]
	s_add_u32 m0, s47, 0xe000
	v_mfma_f32_16x16x32_bf16 v[34:37], v[162:165], v[170:173], v[34:37]
	ds_read_b128 v[170:173], v175 offset:14336
	s_waitcnt lgkmcnt(1)
	v_mfma_f32_16x16x32_bf16 v[30:33], v[150:153], v[166:169], v[30:33]
	global_load_lds_dwordx4 v183, s[100:101]
	v_mfma_f32_16x16x32_bf16 v[26:29], v[154:157], v[166:169], v[26:29]
	v_mfma_f32_16x16x32_bf16 v[22:25], v[158:161], v[166:169], v[22:25]
	v_mfma_f32_16x16x32_bf16 v[18:21], v[162:165], v[166:169], v[18:21]
	s_waitcnt lgkmcnt(0)
	v_mfma_f32_16x16x32_bf16 v[14:17], v[150:153], v[170:173], v[14:17]
	v_mfma_f32_16x16x32_bf16 v[10:13], v[154:157], v[170:173], v[10:13]
	v_mfma_f32_16x16x32_bf16 v[6:9], v[158:161], v[170:173], v[6:9]
	v_mfma_f32_16x16x32_bf16 v[2:5], v[162:165], v[170:173], v[2:5]
	v_add_u32_e32 v162, v174, v144
	ds_read_b128 v[150:153], v162 offset:32768
	ds_read_b128 v[154:157], v162 offset:34816
	ds_read_b128 v[158:161], v162 offset:36864
	ds_read_b128 v[162:165], v162 offset:38912
	v_add_u32_e32 v149, v149, v144
	ds_read_b128 v[166:169], v149
	ds_read_b128 v[170:173], v149 offset:2048
	s_waitcnt lgkmcnt(0)
	v_mfma_f32_16x16x32_bf16 v[126:129], v[150:153], v[166:169], v[126:129]
	s_add_u32 s100, s100, 0x80
	v_mfma_f32_16x16x32_bf16 v[122:125], v[154:157], v[166:169], v[122:125]
	s_addc_u32 s101, s101, 0
	v_mfma_f32_16x16x32_bf16 v[118:121], v[158:161], v[166:169], v[118:121]
	s_add_u32 s22, s22, 0x80
	v_mfma_f32_16x16x32_bf16 v[114:117], v[162:165], v[166:169], v[114:117]
	ds_read_b128 v[166:169], v149 offset:4096
	v_mfma_f32_16x16x32_bf16 v[110:113], v[150:153], v[170:173], v[110:113]
	s_addc_u32 s23, s23, 0
	v_mfma_f32_16x16x32_bf16 v[106:109], v[154:157], v[170:173], v[106:109]
	s_add_i32 s45, s45, 0x10000
	v_mfma_f32_16x16x32_bf16 v[102:105], v[158:161], v[170:173], v[102:105]
	v_mfma_f32_16x16x32_bf16 v[98:101], v[162:165], v[170:173], v[98:101]
	ds_read_b128 v[170:173], v149 offset:6144
	s_waitcnt lgkmcnt(0)
	v_mfma_f32_16x16x32_bf16 v[94:97], v[150:153], v[166:169], v[94:97]
	v_mfma_f32_16x16x32_bf16 v[90:93], v[154:157], v[166:169], v[90:93]
	v_mfma_f32_16x16x32_bf16 v[86:89], v[158:161], v[166:169], v[86:89]
	v_mfma_f32_16x16x32_bf16 v[82:85], v[162:165], v[166:169], v[82:85]
	ds_read_b128 v[166:169], v149 offset:8192
	v_mfma_f32_16x16x32_bf16 v[78:81], v[150:153], v[170:173], v[78:81]
	v_mfma_f32_16x16x32_bf16 v[74:77], v[154:157], v[170:173], v[74:77]
	v_mfma_f32_16x16x32_bf16 v[70:73], v[158:161], v[170:173], v[70:73]
	v_mfma_f32_16x16x32_bf16 v[66:69], v[162:165], v[170:173], v[66:69]
	ds_read_b128 v[170:173], v149 offset:10240
	s_waitcnt lgkmcnt(0)
	v_mfma_f32_16x16x32_bf16 v[62:65], v[150:153], v[166:169], v[62:65]
	v_mfma_f32_16x16x32_bf16 v[58:61], v[154:157], v[166:169], v[58:61]
	v_mfma_f32_16x16x32_bf16 v[54:57], v[158:161], v[166:169], v[54:57]
	v_mfma_f32_16x16x32_bf16 v[50:53], v[162:165], v[166:169], v[50:53]
	ds_read_b128 v[166:169], v149 offset:12288
	v_mfma_f32_16x16x32_bf16 v[46:49], v[150:153], v[170:173], v[46:49]
	v_mfma_f32_16x16x32_bf16 v[42:45], v[154:157], v[170:173], v[42:45]
	v_mfma_f32_16x16x32_bf16 v[38:41], v[158:161], v[170:173], v[38:41]
	v_mfma_f32_16x16x32_bf16 v[34:37], v[162:165], v[170:173], v[34:37]
	ds_read_b128 v[170:173], v149 offset:14336
	s_waitcnt lgkmcnt(0)
	v_mfma_f32_16x16x32_bf16 v[30:33], v[150:153], v[166:169], v[30:33]
	v_mfma_f32_16x16x32_bf16 v[26:29], v[154:157], v[166:169], v[26:29]
	v_mfma_f32_16x16x32_bf16 v[22:25], v[158:161], v[166:169], v[22:25]
	v_mfma_f32_16x16x32_bf16 v[18:21], v[162:165], v[166:169], v[18:21]
	v_mfma_f32_16x16x32_bf16 v[14:17], v[150:153], v[170:173], v[14:17]
	v_mfma_f32_16x16x32_bf16 v[10:13], v[154:157], v[170:173], v[10:13]
	v_mfma_f32_16x16x32_bf16 v[6:9], v[158:161], v[170:173], v[6:9]
	v_mfma_f32_16x16x32_bf16 v[2:5], v[162:165], v[170:173], v[2:5]
	s_cmpk_eq_i32 s22, 0x780
	s_waitcnt vmcnt(0)
	s_barrier
	s_cbranch_scc0 .LBB0_107
	s_branch .LBB0_99

; #define MFMA16(a, b, c) __builtin_amdgcn_mfma_f32_16x16x32_bf16((a), (b), (c), 0, 0, 0)
;     ...
;   for (int kt = 0; kt < nk; ++kt) {
;     const int buf = kt & 1;
;     const char* cA = smem + buf * STAGE + (wm * 32 * MI + r16) * 128;
;     const char* cB = smem + buf * STAGE + 32768 + (wn * 64 + r16) * 128;
; #pragma unroll
;     for (int k2 = 0; k2 < 2; ++k2) {
;       if (k2 == 1 && kt + 1 < nk) STAGE_TILE(buf ^ 1, (kt + 1) * 64)
;       const int po = ((4 * k2 + q4) ^ swz) * 16;
;       bf16x8 bf[4];
; #pragma unroll
;       for (int nt = 0; nt < 4; ++nt) bf[nt] = *(const bf16x8*)(cB + nt * 16 * 128 + po);
;       bf16x8 afc = *(const bf16x8*)(cA + po);
; #pragma unroll
;       for (int a = 0; a < MT; ++a) {
;         bf16x8 afn = afc;
;         if (a + 1 < MT) afn = *(const bf16x8*)(cA + (a + 1) * 16 * 128 + po);
;         __builtin_amdgcn_sched_barrier(0);
; #pragma unroll
;         for (int nt = 0; nt < 4; ++nt) acc[a][nt] = MFMA16(bf[nt], afc, acc[a][nt]);
;         __builtin_amdgcn_sched_barrier(0);
;         afc = afn;
;       }
;     }
;     asm volatile("s_waitcnt vmcnt(0)" ::: "memory");
;     __syncthreads();
;   }
.LBB0_565:
	s_and_b32 s6, s5, 0x10000
	s_add_i32 s7, s6, 0
	v_add_u32_e32 v190, s7, v146
	v_add_u32_e32 v164, v190, v145
	v_add_u32_e32 v163, s7, v147
	ds_read_b128 v[148:151], v164 offset:32768
	ds_read_b128 v[152:155], v164 offset:34816
	ds_read_b128 v[156:159], v164 offset:36864
	ds_read_b128 v[164:167], v164 offset:38912
	v_add_u32_e32 v202, v163, v145
	ds_read_b128 v[168:171], v202
	ds_read_b128 v[172:175], v202 offset:2048
	s_xor_b32 s6, s6, 0x10000
	s_waitcnt lgkmcnt(1)
	v_mfma_f32_16x16x32_bf16 v[126:129], v[148:151], v[168:171], v[126:129]
	v_readfirstlane_b32 s7, v144
	v_mfma_f32_16x16x32_bf16 v[122:125], v[152:155], v[168:171], v[122:125]
	s_nop 0
	v_mfma_f32_16x16x32_bf16 v[118:121], v[156:159], v[168:171], v[118:121]
	s_add_u32 s7, s7, s6
	v_mfma_f32_16x16x32_bf16 v[114:117], v[164:167], v[168:171], v[114:117]
	ds_read_b128 v[168:171], v202 offset:4096
	s_waitcnt lgkmcnt(1)
	v_mfma_f32_16x16x32_bf16 v[110:113], v[148:151], v[172:175], v[110:113]
	s_add_u32 m0, s7, 0x0
	v_mfma_f32_16x16x32_bf16 v[106:109], v[152:155], v[172:175], v[106:109]
	global_load_lds_dwordx4 v176, s[100:101]
	v_mfma_f32_16x16x32_bf16 v[102:105], v[156:159], v[172:175], v[102:105]
	s_add_u32 m0, s7, 0x2000
	v_mfma_f32_16x16x32_bf16 v[98:101], v[164:167], v[172:175], v[98:101]
	ds_read_b128 v[172:175], v202 offset:6144
	s_waitcnt lgkmcnt(1)
	v_mfma_f32_16x16x32_bf16 v[94:97], v[148:151], v[168:171], v[94:97]
	global_load_lds_dwordx4 v177, s[100:101]
	v_mfma_f32_16x16x32_bf16 v[90:93], v[152:155], v[168:171], v[90:93]
	s_add_u32 m0, s7, 0x4000
	v_mfma_f32_16x16x32_bf16 v[86:89], v[156:159], v[168:171], v[86:89]
	global_load_lds_dwordx4 v178, s[100:101]
	v_mfma_f32_16x16x32_bf16 v[82:85], v[164:167], v[168:171], v[82:85]
	ds_read_b128 v[168:171], v202 offset:8192
	s_waitcnt lgkmcnt(1)
	v_mfma_f32_16x16x32_bf16 v[78:81], v[148:151], v[172:175], v[78:81]
	s_add_u32 m0, s7, 0x6000
	v_mfma_f32_16x16x32_bf16 v[74:77], v[152:155], v[172:175], v[74:77]
	global_load_lds_dwordx4 v179, s[100:101]
	v_mfma_f32_16x16x32_bf16 v[70:73], v[156:159], v[172:175], v[70:73]
	s_add_u32 m0, s7, 0x8000
	v_mfma_f32_16x16x32_bf16 v[66:69], v[164:167], v[172:175], v[66:69]
	ds_read_b128 v[172:175], v202 offset:10240
	s_waitcnt lgkmcnt(1)
	v_mfma_f32_16x16x32_bf16 v[62:65], v[148:151], v[168:171], v[62:65]
	global_load_lds_dwordx4 v180, s[100:101]
	v_mfma_f32_16x16x32_bf16 v[58:61], v[152:155], v[168:171], v[58:61]
	s_add_u32 m0, s7, 0xa000
	v_mfma_f32_16x16x32_bf16 v[54:57], v[156:159], v[168:171], v[54:57]
	global_load_lds_dwordx4 v181, s[100:101]
	v_mfma_f32_16x16x32_bf16 v[50:53], v[164:167], v[168:171], v[50:53]
	ds_read_b128 v[168:171], v202 offset:12288
	s_waitcnt lgkmcnt(1)
	v_mfma_f32_16x16x32_bf16 v[46:49], v[148:151], v[172:175], v[46:49]
	s_add_u32 m0, s7, 0xc000
	v_mfma_f32_16x16x32_bf16 v[42:45], v[152:155], v[172:175], v[42:45]
	global_load_lds_dwordx4 v182, s[100:101]
	v_mfma_f32_16x16x32_bf16 v[38:41], v[156:159], v[172:175], v[38:41]
	s_add_u32 m0, s7, 0xe000
	v_mfma_f32_16x16x32_bf16 v[34:37], v[164:167], v[172:175], v[34:37]
	ds_read_b128 v[172:175], v202 offset:14336
	s_waitcnt lgkmcnt(1)
	v_mfma_f32_16x16x32_bf16 v[30:33], v[148:151], v[168:171], v[30:33]
	global_load_lds_dwordx4 v183, s[100:101]
	v_mfma_f32_16x16x32_bf16 v[26:29], v[152:155], v[168:171], v[26:29]
	v_mfma_f32_16x16x32_bf16 v[22:25], v[156:159], v[168:171], v[22:25]
	v_mfma_f32_16x16x32_bf16 v[18:21], v[164:167], v[168:171], v[18:21]
	s_waitcnt lgkmcnt(0)
	v_mfma_f32_16x16x32_bf16 v[14:17], v[148:151], v[172:175], v[14:17]
	v_mfma_f32_16x16x32_bf16 v[10:13], v[152:155], v[172:175], v[10:13]
	v_mfma_f32_16x16x32_bf16 v[6:9], v[156:159], v[172:175], v[6:9]
	v_mfma_f32_16x16x32_bf16 v[2:5], v[164:167], v[172:175], v[2:5]
	v_add_u32_e32 v160, v190, v143
	ds_read_b128 v[148:151], v160 offset:32768
	ds_read_b128 v[152:155], v160 offset:34816
	ds_read_b128 v[156:159], v160 offset:36864
	ds_read_b128 v[164:167], v160 offset:38912
	v_add_u32_e32 v160, v163, v143
	ds_read_b128 v[168:171], v160
	ds_read_b128 v[172:175], v160 offset:2048
	s_waitcnt lgkmcnt(0)
	v_mfma_f32_16x16x32_bf16 v[126:129], v[148:151], v[168:171], v[126:129]
	s_add_u32 s100, s100, 0x80
	v_mfma_f32_16x16x32_bf16 v[122:125], v[152:155], v[168:171], v[122:125]
	s_addc_u32 s101, s101, 0
	v_mfma_f32_16x16x32_bf16 v[118:121], v[156:159], v[168:171], v[118:121]
	s_add_u32 s2, s2, 0x80
	v_mfma_f32_16x16x32_bf16 v[114:117], v[164:167], v[168:171], v[114:117]
	ds_read_b128 v[168:171], v160 offset:4096
	v_mfma_f32_16x16x32_bf16 v[110:113], v[148:151], v[172:175], v[110:113]
	s_addc_u32 s3, s3, 0
	v_mfma_f32_16x16x32_bf16 v[106:109], v[152:155], v[172:175], v[106:109]
	s_add_i32 s5, s5, 0x10000
	v_mfma_f32_16x16x32_bf16 v[102:105], v[156:159], v[172:175], v[102:105]
	v_mfma_f32_16x16x32_bf16 v[98:101], v[164:167], v[172:175], v[98:101]
	ds_read_b128 v[172:175], v160 offset:6144
	s_waitcnt lgkmcnt(0)
	v_mfma_f32_16x16x32_bf16 v[94:97], v[148:151], v[168:171], v[94:97]
	v_mfma_f32_16x16x32_bf16 v[90:93], v[152:155], v[168:171], v[90:93]
	v_mfma_f32_16x16x32_bf16 v[86:89], v[156:159], v[168:171], v[86:89]
	v_mfma_f32_16x16x32_bf16 v[82:85], v[164:167], v[168:171], v[82:85]
	ds_read_b128 v[168:171], v160 offset:8192
	v_mfma_f32_16x16x32_bf16 v[78:81], v[148:151], v[172:175], v[78:81]
	v_mfma_f32_16x16x32_bf16 v[74:77], v[152:155], v[172:175], v[74:77]
	v_mfma_f32_16x16x32_bf16 v[70:73], v[156:159], v[172:175], v[70:73]
	v_mfma_f32_16x16x32_bf16 v[66:69], v[164:167], v[172:175], v[66:69]
	ds_read_b128 v[172:175], v160 offset:10240
	s_waitcnt lgkmcnt(0)
	v_mfma_f32_16x16x32_bf16 v[62:65], v[148:151], v[168:171], v[62:65]
	v_mfma_f32_16x16x32_bf16 v[58:61], v[152:155], v[168:171], v[58:61]
	v_mfma_f32_16x16x32_bf16 v[54:57], v[156:159], v[168:171], v[54:57]
	v_mfma_f32_16x16x32_bf16 v[50:53], v[164:167], v[168:171], v[50:53]
	ds_read_b128 v[168:171], v160 offset:12288
	v_mfma_f32_16x16x32_bf16 v[46:49], v[148:151], v[172:175], v[46:49]
	v_mfma_f32_16x16x32_bf16 v[42:45], v[152:155], v[172:175], v[42:45]
	v_mfma_f32_16x16x32_bf16 v[38:41], v[156:159], v[172:175], v[38:41]
	v_mfma_f32_16x16x32_bf16 v[34:37], v[164:167], v[172:175], v[34:37]
	ds_read_b128 v[172:175], v160 offset:14336
	s_waitcnt lgkmcnt(0)
	v_mfma_f32_16x16x32_bf16 v[30:33], v[148:151], v[168:171], v[30:33]
	v_mfma_f32_16x16x32_bf16 v[26:29], v[152:155], v[168:171], v[26:29]
	v_mfma_f32_16x16x32_bf16 v[22:25], v[156:159], v[168:171], v[22:25]
	v_mfma_f32_16x16x32_bf16 v[18:21], v[164:167], v[168:171], v[18:21]
	v_mfma_f32_16x16x32_bf16 v[14:17], v[148:151], v[172:175], v[14:17]
	v_mfma_f32_16x16x32_bf16 v[10:13], v[152:155], v[172:175], v[10:13]
	v_mfma_f32_16x16x32_bf16 v[6:9], v[156:159], v[172:175], v[6:9]
	v_mfma_f32_16x16x32_bf16 v[2:5], v[164:167], v[172:175], v[2:5]
	s_cmpk_eq_i32 s2, 0x780
	s_waitcnt vmcnt(0)
	s_barrier
; #define MFMA16(a, b, c) __builtin_amdgcn_mfma_f32_16x16x32_bf16((a), (b), (c), 0, 0, 0)
;     ...
;   for (int kt = 0; kt < nk; ++kt) {
;     const int buf = kt & 1;
;     const char* cA = smem + buf * STAGE + (wm * 32 * MI + r16) * 128;
;     const char* cB = smem + buf * STAGE + 32768 + (wn * 64 + r16) * 128;
; #pragma unroll
;     for (int k2 = 0; k2 < 2; ++k2) {
;       if (k2 == 1 && kt + 1 < nk) STAGE_TILE(buf ^ 1, (kt + 1) * 64)
;       const int po = ((4 * k2 + q4) ^ swz) * 16;
;       bf16x8 bf[4];
; #pragma unroll
;       for (int nt = 0; nt < 4; ++nt) bf[nt] = *(const bf16x8*)(cB + nt * 16 * 128 + po);
;       bf16x8 afc = *(const bf16x8*)(cA + po);
; #pragma unroll
;       for (int a = 0; a < MT; ++a) {
;         bf16x8 afn = afc;
;         if (a + 1 < MT) afn = *(const bf16x8*)(cA + (a + 1) * 16 * 128 + po);
;         __builtin_amdgcn_sched_barrier(0);
; #pragma unroll
;         for (int nt = 0; nt < 4; ++nt) acc[a][nt] = MFMA16(bf[nt], afc, acc[a][nt]);
;         __builtin_amdgcn_sched_barrier(0);
;         afc = afn;
;       }
;     }
;     asm volatile("s_waitcnt vmcnt(0)" ::: "memory");
;     __syncthreads();
;   }
; DI void phase_win(char* smem, const Params& p, int layer) {
;     ...
;   auto ep = [&](int row, int cbw, int q4, const f32x4& c0, const f32x4& c1, const f32x4& c2, const f32x4& c3) {
;     if (cbw > 2432) return;
;     const int b = row / TT, t = row - b * TT;
	s_cbranch_scc0 .LBB0_565
	s_add_i32 s2, 0, 0x10000
	v_add_u32_e32 v138, s2, v147
	v_readlane_b32 s2, v254, 18
	s_nop 1
	v_add_u32_e32 v139, s2, v146
	v_add_u32_e32 v144, v139, v145
	ds_read_b128 v[130:133], v144
	ds_read_b128 v[134:137], v144 offset:2048
	ds_read_b128 v[146:149], v144 offset:4096
	ds_read_b128 v[150:153], v144 offset:6144
	v_add_u32_e32 v144, v138, v145
	ds_read_b128 v[154:157], v144
	ds_read_b128 v[158:161], v144 offset:2048
	s_waitcnt lgkmcnt(1)
	v_mfma_f32_16x16x32_bf16 v[122:125], v[134:137], v[154:157], v[122:125]
	v_mfma_f32_16x16x32_bf16 v[118:121], v[146:149], v[154:157], v[118:121]
	v_mfma_f32_16x16x32_bf16 v[114:117], v[150:153], v[154:157], v[114:117]
	v_mfma_f32_16x16x32_bf16 v[126:129], v[130:133], v[154:157], v[126:129]
	ds_read_b128 v[154:157], v144 offset:4096
	s_waitcnt lgkmcnt(1)
	v_mfma_f32_16x16x32_bf16 v[110:113], v[130:133], v[158:161], v[110:113]
	v_mfma_f32_16x16x32_bf16 v[106:109], v[134:137], v[158:161], v[106:109]
	v_mfma_f32_16x16x32_bf16 v[102:105], v[146:149], v[158:161], v[102:105]
	v_mfma_f32_16x16x32_bf16 v[98:101], v[150:153], v[158:161], v[98:101]
	ds_read_b128 v[158:161], v144 offset:6144
	s_waitcnt lgkmcnt(1)
	v_mfma_f32_16x16x32_bf16 v[94:97], v[130:133], v[154:157], v[94:97]
	v_mfma_f32_16x16x32_bf16 v[90:93], v[134:137], v[154:157], v[90:93]
	v_mfma_f32_16x16x32_bf16 v[86:89], v[146:149], v[154:157], v[86:89]
	v_mfma_f32_16x16x32_bf16 v[82:85], v[150:153], v[154:157], v[82:85]
	ds_read_b128 v[154:157], v144 offset:8192
	s_waitcnt lgkmcnt(1)
	v_mfma_f32_16x16x32_bf16 v[78:81], v[130:133], v[158:161], v[78:81]
	v_mfma_f32_16x16x32_bf16 v[74:77], v[134:137], v[158:161], v[74:77]
	v_mfma_f32_16x16x32_bf16 v[70:73], v[146:149], v[158:161], v[70:73]
	v_mfma_f32_16x16x32_bf16 v[66:69], v[150:153], v[158:161], v[66:69]
	ds_read_b128 v[158:161], v144 offset:10240
	s_waitcnt lgkmcnt(1)
	v_mfma_f32_16x16x32_bf16 v[62:65], v[130:133], v[154:157], v[62:65]
	v_mfma_f32_16x16x32_bf16 v[58:61], v[134:137], v[154:157], v[58:61]
	v_mfma_f32_16x16x32_bf16 v[54:57], v[146:149], v[154:157], v[54:57]
	v_mfma_f32_16x16x32_bf16 v[50:53], v[150:153], v[154:157], v[50:53]
	ds_read_b128 v[154:157], v144 offset:12288
	s_waitcnt lgkmcnt(1)
	v_mfma_f32_16x16x32_bf16 v[46:49], v[130:133], v[158:161], v[46:49]
	v_mfma_f32_16x16x32_bf16 v[42:45], v[134:137], v[158:161], v[42:45]
	v_mfma_f32_16x16x32_bf16 v[38:41], v[146:149], v[158:161], v[38:41]
	v_mfma_f32_16x16x32_bf16 v[34:37], v[150:153], v[158:161], v[34:37]
	ds_read_b128 v[158:161], v144 offset:14336
	s_waitcnt lgkmcnt(1)
	v_mfma_f32_16x16x32_bf16 v[30:33], v[130:133], v[154:157], v[30:33]
	v_mfma_f32_16x16x32_bf16 v[26:29], v[134:137], v[154:157], v[26:29]
	v_mfma_f32_16x16x32_bf16 v[22:25], v[146:149], v[154:157], v[22:25]
	v_mfma_f32_16x16x32_bf16 v[18:21], v[150:153], v[154:157], v[18:21]
	s_waitcnt lgkmcnt(0)
	v_mfma_f32_16x16x32_bf16 v[14:17], v[130:133], v[158:161], v[14:17]
	v_mfma_f32_16x16x32_bf16 v[10:13], v[134:137], v[158:161], v[10:13]
	v_mfma_f32_16x16x32_bf16 v[6:9], v[146:149], v[158:161], v[6:9]
	v_mfma_f32_16x16x32_bf16 v[2:5], v[150:153], v[158:161], v[2:5]
	v_add_u32_e32 v130, v139, v143
	ds_read_b128 v[134:137], v130
	ds_read_b128 v[144:147], v130 offset:2048
	ds_read_b128 v[148:151], v130 offset:4096
	ds_read_b128 v[152:155], v130 offset:6144
	v_add_u32_e32 v138, v138, v143
	ds_read_b128 v[156:159], v138
	ds_read_b128 v[164:167], v138 offset:2048
	s_waitcnt lgkmcnt(1)
	v_mfma_f32_16x16x32_bf16 v[130:133], v[134:137], v[156:159], v[126:129]
	v_mfma_f32_16x16x32_bf16 v[122:125], v[144:147], v[156:159], v[122:125]
	v_mfma_f32_16x16x32_bf16 v[118:121], v[148:151], v[156:159], v[118:121]
	v_mfma_f32_16x16x32_bf16 v[114:117], v[152:155], v[156:159], v[114:117]
	ds_read_b128 v[126:129], v138 offset:4096
	s_waitcnt lgkmcnt(1)
	v_mfma_f32_16x16x32_bf16 v[110:113], v[134:137], v[164:167], v[110:113]
	v_mfma_f32_16x16x32_bf16 v[106:109], v[144:147], v[164:167], v[106:109]
	v_mfma_f32_16x16x32_bf16 v[102:105], v[148:151], v[164:167], v[102:105]
	v_mfma_f32_16x16x32_bf16 v[98:101], v[152:155], v[164:167], v[98:101]
	ds_read_b128 v[156:159], v138 offset:6144
	s_waitcnt lgkmcnt(1)
	v_mfma_f32_16x16x32_bf16 v[94:97], v[134:137], v[126:129], v[94:97]
	v_mfma_f32_16x16x32_bf16 v[90:93], v[144:147], v[126:129], v[90:93]
	v_mfma_f32_16x16x32_bf16 v[86:89], v[148:151], v[126:129], v[86:89]
	v_mfma_f32_16x16x32_bf16 v[82:85], v[152:155], v[126:129], v[82:85]
	ds_read_b128 v[126:129], v138 offset:8192
	s_waitcnt lgkmcnt(1)
	v_mfma_f32_16x16x32_bf16 v[78:81], v[134:137], v[156:159], v[78:81]
	v_mfma_f32_16x16x32_bf16 v[74:77], v[144:147], v[156:159], v[74:77]
	v_mfma_f32_16x16x32_bf16 v[70:73], v[148:151], v[156:159], v[70:73]
	v_mfma_f32_16x16x32_bf16 v[66:69], v[152:155], v[156:159], v[66:69]
	ds_read_b128 v[156:159], v138 offset:10240
	s_waitcnt lgkmcnt(1)
	v_mfma_f32_16x16x32_bf16 v[62:65], v[134:137], v[126:129], v[62:65]
	v_mfma_f32_16x16x32_bf16 v[58:61], v[144:147], v[126:129], v[58:61]
	v_mfma_f32_16x16x32_bf16 v[54:57], v[148:151], v[126:129], v[54:57]
	v_mfma_f32_16x16x32_bf16 v[50:53], v[152:155], v[126:129], v[50:53]
	ds_read_b128 v[126:129], v138 offset:12288
	s_waitcnt lgkmcnt(1)
	v_mfma_f32_16x16x32_bf16 v[46:49], v[134:137], v[156:159], v[46:49]
	v_mfma_f32_16x16x32_bf16 v[42:45], v[144:147], v[156:159], v[42:45]
	v_mfma_f32_16x16x32_bf16 v[38:41], v[148:151], v[156:159], v[38:41]
	v_mfma_f32_16x16x32_bf16 v[34:37], v[152:155], v[156:159], v[34:37]
	ds_read_b128 v[156:159], v138 offset:14336
	s_waitcnt lgkmcnt(1)
	v_mfma_f32_16x16x32_bf16 v[30:33], v[134:137], v[126:129], v[30:33]
	v_mfma_f32_16x16x32_bf16 v[26:29], v[144:147], v[126:129], v[26:29]
	v_mfma_f32_16x16x32_bf16 v[22:25], v[148:151], v[126:129], v[22:25]
	v_mfma_f32_16x16x32_bf16 v[18:21], v[152:155], v[126:129], v[18:21]
	s_waitcnt lgkmcnt(0)
	v_mfma_f32_16x16x32_bf16 v[14:17], v[134:137], v[156:159], v[14:17]
	v_mfma_f32_16x16x32_bf16 v[10:13], v[144:147], v[156:159], v[10:13]
	v_mfma_f32_16x16x32_bf16 v[6:9], v[148:151], v[156:159], v[6:9]
	v_mfma_f32_16x16x32_bf16 v[2:5], v[152:155], v[156:159], v[2:5]
	s_waitcnt vmcnt(0)
	v_lshl_or_b32 v190, v142, 6, s22
	s_movk_i32 s2, 0x981
	v_cmp_gt_i32_e32 vcc, s2, v190
	s_barrier
; DI bf16_t f2bf(float x) { return (bf16_t)(pack2(x, 0.f) & 0xffffu); }
; DI void phase_win(char* smem, const Params& p, int layer) {
;     ...
;   auto ep = [&](int row, int cbw, int q4, const f32x4& c0, const f32x4& c1, const f32x4& c2, const f32x4& c3) {
;     if (cbw > 2432) return;
;     const int b = row / TT, t = row - b * TT;
;     const bool lat = t >= CTXL;
;     const int pos = t - CTXL;
;     float v[16] = {c0[0], c0[1], c0[2], c0[3], c1[0], c1[1], c1[2], c1[3], c2[0], c2[1], c2[2], c2[3], c3[0], c3[1], c3[2], c3[3]};
;     if (cbw >= 640 && cbw < 768) {
;       bf16_t* vp = p.VsT + ((size_t)(b * 2 + ((cbw - 640) >> 6)) * 64 + q4 * 16) * TT + t;
; #pragma unroll
;       for (int i = 0; i < 16; ++i) vp[(size_t)i * TT] = f2bf(v[i]);
;       return;
;     }
;     const bool r16 = cbw >= 256 && cbw < 640, rkr = cbw == 2432;
;     if (rkr && q4 >= 2) return;
;     if (lat && (r16 || rkr)) {
;       const int a = r16 ? (q4 >> 1) : q4;
;       const int pa = a ? (pos & 63) : (pos >> 6);
;       const float* tab = r16 ? p.ropeS + 2 * (pa * 16 + (q4 & 1) * 8) : p.ropeM + 2 * (pa * 8);
; #pragma unroll
;       for (int k = 0; k < 4; ++k) {
;         const float4 cs = *(const float4*)(tab + 4 * k);
;         const float x0 = v[4 * k], x1 = v[4 * k + 1], x2 = v[4 * k + 2], x3 = v[4 * k + 3];
;         v[4 * k] = x0 * cs.x - x1 * cs.y; v[4 * k + 1] = x1 * cs.x + x0 * cs.y;
;         v[4 * k + 2] = x2 * cs.z - x3 * cs.w; v[4 * k + 3] = x3 * cs.z + x2 * cs.w;
;       }
;     }
	s_and_saveexec_b64 s[96:97], vcc
	s_cbranch_execz .LBB0_557
	v_or_b32_e32 v126, s4, v162
	v_lshl_add_u32 v136, v141, 7, v126
	v_and_b32_e32 v126, 0xffffff80, v190
	s_movk_i32 s2, 0x280
	v_cmp_ne_u32_e64 s[16:17], s2, v126
	s_movk_i32 s2, 0x27f
	v_cmp_lt_i32_e64 s[4:5], s2, v190
	s_movk_i32 s2, 0x980
	v_cmp_ne_u32_e64 s[8:9], s2, v190
	v_cmp_gt_u32_e64 s[6:7], 2, v140
	v_add_u32_e32 v126, 0xffffff00, v190
	v_cmp_eq_u32_e32 vcc, s2, v190
	s_or_b64 s[2:3], s[8:9], s[6:7]
	s_movk_i32 s6, 0x180
	v_cmp_gt_u32_e64 s[12:13], s6, v126
	s_or_b64 s[86:87], vcc, s[12:13]
	v_lshrrev_b32_e32 v160, 6, v126
	v_cndmask_b32_e64 v127, 0, 1, s[12:13]
	v_lshrrev_b32_e32 v127, v127, v140
	v_cmp_eq_u32_e64 s[14:15], 0, v127
	v_add_u32_e32 v127, 0xfffffe00, v190
	v_mul_hi_i32 v126, v136, s1
	s_cmp_eq_u32 s10, 1
	v_lshrrev_b32_e32 v159, 6, v127
	v_lshrrev_b32_e32 v127, 31, v126
	v_ashrrev_i32_e32 v126, 11, v126
	v_lshlrev_b32_e32 v158, 4, v140
	s_movk_i32 s6, 0x1ff
	s_cselect_b64 s[94:95], -1, 0
	s_movk_i32 s10, 0xff
	s_cmpk_gt_u32 s22, 0x7ff
	v_add_u32_e32 v139, v126, v127
	v_and_b32_e32 v161, 16, v158
	v_cmp_lt_i32_e64 s[6:7], s6, v190
	v_cmp_lt_i32_e64 s[10:11], s10, v190
	s_cselect_b64 s[22:23], -1, 0
	v_ashrrev_i32_e32 v135, 31, v190
	v_mov_b32_e32 v134, v190
	v_mad_i32_i24 v138, v139, s80, v136
	s_and_saveexec_b64 s[30:31], s[16:17]
	s_xor_b64 s[30:31], exec, s[30:31]
	s_cbranch_execz .LBB0_594
	s_and_saveexec_b64 s[52:53], s[2:3]
	s_cbranch_execz .LBB0_593
	s_movk_i32 s45, 0xff
	v_cmp_lt_i32_e32 vcc, s45, v138
	s_and_b64 s[46:47], s[86:87], vcc
	v_mov_b32_e32 v140, v131
	v_mov_b32_e32 v141, v133
	v_mov_b32_e32 v142, v123
	v_mov_b32_e32 v143, v125
	v_mov_b32_e32 v144, v119
	v_mov_b32_e32 v145, v121
	v_mov_b32_e32 v154, v115
	v_mov_b32_e32 v155, v117
	v_mov_b32_e32 v146, v130
	v_mov_b32_e32 v147, v132
	v_mov_b32_e32 v148, v122
	v_mov_b32_e32 v149, v124
	v_mov_b32_e32 v150, v118
	v_mov_b32_e32 v151, v120
	v_mov_b32_e32 v152, v114
	v_mov_b32_e32 v153, v116
	s_and_saveexec_b64 s[54:55], s[46:47]
	s_cbranch_execz .LBB0_571
	v_readlane_b32 s46, v252, 1
	v_cndmask_b32_e64 v128, v238, v240, s[12:13]
	v_mov_b32_e32 v129, v191
	v_readlane_b32 s47, v252, 2
	v_add_u32_e32 v126, 0xffffff00, v138
	v_lshrrev_b32_e32 v126, 6, v126
	v_lshl_add_u64 v[128:129], s[46:47], 0, v[128:129]
	global_load_dwordx2 v[128:129], v[128:129], off
	v_cndmask_b32_e64 v126, v162, v126, s[14:15]
	v_lshlrev_b32_e32 v127, 4, v126
	v_lshl_or_b32 v126, v126, 5, v161
	v_cndmask_b32_e64 v126, v127, v126, s[12:13]
	v_mov_b32_e32 v127, v191
	v_mov_b32_e32 v182, v130
	v_mov_b32_e32 v183, v133
	v_mov_b32_e32 v130, v131
	v_mov_b32_e32 v131, v132
	s_waitcnt vmcnt(0)
	v_lshl_add_u64 v[156:157], v[126:127], 2, v[128:129]
	global_load_dwordx4 v[126:129], v[156:157], off offset:48
	global_load_dwordx4 v[164:167], v[156:157], off offset:32
	global_load_dwordx4 v[168:171], v[156:157], off offset:16
	global_load_dwordx4 v[172:175], v[156:157], off
	s_waitcnt vmcnt(3)
	v_mov_b32_e32 v156, v127
	s_waitcnt vmcnt(2)
	v_mov_b32_e32 v180, v165
	s_waitcnt vmcnt(1)
	v_mov_b32_e32 v178, v169
	s_waitcnt vmcnt(0)
	v_mov_b32_e32 v132, v172
	v_mov_b32_e32 v133, v175
	v_mov_b32_e32 v176, v173
	v_mov_b32_e32 v177, v174
	v_pk_mul_f32 v[130:131], v[130:131], v[132:133]
	v_mov_b32_e32 v132, v173
	v_pk_mul_f32 v[132:133], v[140:141], v[132:133]
	v_pk_fma_f32 v[140:141], v[182:183], v[176:177], v[130:131]
	v_mov_b32_e32 v130, v122
	v_mov_b32_e32 v131, v125
	v_mov_b32_e32 v122, v123
	v_mov_b32_e32 v123, v124
	v_mov_b32_e32 v124, v168
	v_mov_b32_e32 v125, v171
	v_mov_b32_e32 v179, v170
	v_pk_mul_f32 v[122:123], v[122:123], v[124:125]
	v_mov_b32_e32 v124, v169
	v_pk_mul_f32 v[124:125], v[142:143], v[124:125]
	v_pk_fma_f32 v[142:143], v[130:131], v[178:179], v[122:123]
	v_mov_b32_e32 v122, v118
	v_mov_b32_e32 v123, v121
	v_mov_b32_e32 v118, v119
	v_mov_b32_e32 v119, v120
	v_mov_b32_e32 v120, v164
	v_mov_b32_e32 v121, v167
	v_mov_b32_e32 v181, v166
	v_pk_mul_f32 v[118:119], v[118:119], v[120:121]
	v_mov_b32_e32 v120, v165
	v_pk_mul_f32 v[120:121], v[144:145], v[120:121]
	v_pk_fma_f32 v[144:145], v[122:123], v[180:181], v[118:119]
	v_mov_b32_e32 v118, v114
	v_mov_b32_e32 v119, v117
	v_mov_b32_e32 v114, v115
	v_mov_b32_e32 v115, v116
	v_mov_b32_e32 v116, v126
	v_mov_b32_e32 v117, v129
	v_pk_mul_f32 v[114:115], v[114:115], v[116:117]
	v_mov_b32_e32 v116, v127
	v_mov_b32_e32 v157, v128
	v_mov_b32_e32 v173, v174
	v_mov_b32_e32 v169, v170
	v_mov_b32_e32 v165, v166
	v_pk_mul_f32 v[116:117], v[154:155], v[116:117]
	v_mov_b32_e32 v127, v128
	v_pk_fma_f32 v[146:147], v[146:147], v[172:173], v[132:133] neg_lo:[0,0,1] neg_hi:[0,0,1]
	v_pk_fma_f32 v[148:149], v[148:149], v[168:169], v[124:125] neg_lo:[0,0,1] neg_hi:[0,0,1]
	v_pk_fma_f32 v[150:151], v[150:151], v[164:165], v[120:121] neg_lo:[0,0,1] neg_hi:[0,0,1]
	v_pk_fma_f32 v[152:153], v[152:153], v[126:127], v[116:117] neg_lo:[0,0,1] neg_hi:[0,0,1]
	v_pk_fma_f32 v[154:155], v[118:119], v[156:157], v[114:115]
